# K-loops of GEMM1/K/V: LDS-DMA addresses formed on the scalar side (saddr+voffset, k-step added in place to the bases), 16 VALU adds per iteration removed from the partner of the MFMA wave
# speedup vs baseline: 1.0016x; 1.0016x over previous
.LBB0_202:
	s_add_u32 s2, s6, 0xfffc0080
	s_addc_u32 s3, s7, -1
	s_add_i32 s66, 0, 0x10000
	s_cmp_eq_u32 s89, 12
	s_cselect_b32 s57, s20, s3
	s_cselect_b32 s56, s21, s2
	v_add_u32_e32 v148, s66, v151
	s_cselect_b32 s91, s49, s88
	s_cselect_b32 s90, s51, s62
	s_add_i32 s2, 0, 0x14000
	ds_read_b128 v[144:147], v148
	ds_read_b128 v[164:167], v148 offset:1024
	ds_read_b128 v[176:179], v148 offset:2048
	ds_read_b128 v[180:183], v148 offset:3072
	v_add_u32_e32 v148, s2, v151
	ds_read_b128 v[184:187], v148
	ds_read_b128 v[188:191], v148 offset:1024
	ds_read_b128 v[192:195], v148 offset:2048
	ds_read_b128 v[196:199], v148 offset:3072
	s_add_i32 m0, s17, 0xc000
	ds_read_b128 v[200:203], v153
	ds_read_b128 v[204:207], v153 offset:1024
	ds_read_b128 v[208:211], v153 offset:2048
	ds_read_b128 v[212:215], v153 offset:3072
	ds_read_b128 v[216:219], v153 offset:4096
	ds_read_b128 v[220:223], v153 offset:5120
	ds_read_b128 v[224:227], v153 offset:6144
	ds_read_b128 v[228:231], v153 offset:7168
	global_load_lds_dwordx4 v140, s[6:7]
	s_add_i32 m0, s17, 0xe000
	s_nop 0
	global_load_lds_dwordx4 v142, s[6:7]
	s_waitcnt vmcnt(8)
	s_waitcnt lgkmcnt(0)
	v_mfma_f32_16x16x32_f16 v[128:131], v[144:147], v[200:203], v[128:131]
	v_mfma_f32_16x16x32_f16 v[124:127], v[176:179], v[200:203], v[124:127]
	v_mfma_f32_16x16x32_f16 v[112:115], v[144:147], v[208:211], v[112:115]
	v_mfma_f32_16x16x32_f16 v[108:111], v[176:179], v[208:211], v[108:111]
	s_barrier
	s_setprio 1
	s_waitcnt lgkmcnt(0)
	v_mfma_f32_16x16x32_f16 v[96:99], v[144:147], v[216:219], v[96:99]
	v_mfma_f32_16x16x32_f16 v[92:95], v[176:179], v[216:219], v[92:95]
	v_mfma_f32_16x16x32_f16 v[80:83], v[144:147], v[224:227], v[80:83]
	v_mfma_f32_16x16x32_f16 v[76:79], v[176:179], v[224:227], v[76:79]
	v_mfma_f32_16x16x32_f16 v[128:131], v[164:167], v[204:207], v[128:131]
	v_mfma_f32_16x16x32_f16 v[124:127], v[180:183], v[204:207], v[124:127]
	v_mfma_f32_16x16x32_f16 v[112:115], v[164:167], v[212:215], v[112:115]
	v_mfma_f32_16x16x32_f16 v[108:111], v[180:183], v[212:215], v[108:111]
	v_mfma_f32_16x16x32_f16 v[96:99], v[164:167], v[220:223], v[96:99]
	v_mfma_f32_16x16x32_f16 v[92:95], v[180:183], v[220:223], v[92:95]
	v_mfma_f32_16x16x32_f16 v[80:83], v[164:167], v[228:231], v[80:83]
	v_mfma_f32_16x16x32_f16 v[76:79], v[180:183], v[228:231], v[76:79]
	s_setprio 0
	s_setprio 1
	v_mfma_f32_16x16x32_f16 v[120:123], v[184:187], v[200:203], v[120:123]
	v_mfma_f32_16x16x32_f16 v[116:119], v[192:195], v[200:203], v[116:119]
	v_mfma_f32_16x16x32_f16 v[104:107], v[184:187], v[208:211], v[104:107]
	v_mfma_f32_16x16x32_f16 v[100:103], v[192:195], v[208:211], v[100:103]
	v_mfma_f32_16x16x32_f16 v[88:91], v[184:187], v[216:219], v[88:91]
	v_mfma_f32_16x16x32_f16 v[84:87], v[192:195], v[216:219], v[84:87]
	v_mfma_f32_16x16x32_f16 v[72:75], v[184:187], v[224:227], v[72:75]
	v_mfma_f32_16x16x32_f16 v[68:71], v[192:195], v[224:227], v[68:71]
	v_mfma_f32_16x16x32_f16 v[120:123], v[188:191], v[204:207], v[120:123]
	v_mfma_f32_16x16x32_f16 v[116:119], v[196:199], v[204:207], v[116:119]
	v_mfma_f32_16x16x32_f16 v[104:107], v[188:191], v[212:215], v[104:107]
	v_mfma_f32_16x16x32_f16 v[100:103], v[196:199], v[212:215], v[100:103]
	v_mfma_f32_16x16x32_f16 v[88:91], v[188:191], v[220:223], v[88:91]
	v_mfma_f32_16x16x32_f16 v[84:87], v[196:199], v[220:223], v[84:87]
	v_mfma_f32_16x16x32_f16 v[72:75], v[188:191], v[228:231], v[72:75]
	v_mfma_f32_16x16x32_f16 v[68:71], v[196:199], v[228:231], v[68:71]
	s_setprio 0
	s_barrier
	s_add_i32 s3, s66, s16
	s_mov_b32 m0, s3
	ds_read_b128 v[200:203], v153 offset:16384
	ds_read_b128 v[204:207], v153 offset:17408
	ds_read_b128 v[208:211], v153 offset:18432
	ds_read_b128 v[212:215], v153 offset:19456
	ds_read_b128 v[216:219], v153 offset:20480
	ds_read_b128 v[220:223], v153 offset:21504
	ds_read_b128 v[224:227], v153 offset:22528
	ds_read_b128 v[228:231], v153 offset:23552
	global_load_lds_dwordx4 v2, s[90:91]
	s_add_i32 m0, s3, 0x2000
	s_add_i32 s2, s2, s16
	global_load_lds_dwordx4 v0, s[90:91]
	s_mov_b32 m0, s2
	s_nop 0
	global_load_lds_dwordx4 v136, s[90:91]
	s_add_i32 m0, s2, 0x2000
	s_nop 0
	global_load_lds_dwordx4 v132, s[90:91]
	s_mov_b32 m0, s17
	s_nop 0
	global_load_lds_dwordx4 v138, s[56:57]
	s_mov_b32 m0, s28
	s_nop 0
	global_load_lds_dwordx4 v134, s[56:57]
	s_waitcnt vmcnt(8)
	s_waitcnt lgkmcnt(0)
	v_mfma_f32_16x16x32_f16 v[64:67], v[144:147], v[200:203], v[64:67]
	v_mfma_f32_16x16x32_f16 v[60:63], v[176:179], v[200:203], v[60:63]
	v_mfma_f32_16x16x32_f16 v[48:51], v[144:147], v[208:211], v[48:51]
	v_mfma_f32_16x16x32_f16 v[44:47], v[176:179], v[208:211], v[44:47]
	s_barrier
	s_setprio 1
	s_waitcnt lgkmcnt(0)
	v_mfma_f32_16x16x32_f16 v[32:35], v[144:147], v[216:219], v[32:35]
	v_mfma_f32_16x16x32_f16 v[28:31], v[176:179], v[216:219], v[28:31]
	v_mfma_f32_16x16x32_f16 v[16:19], v[144:147], v[224:227], v[16:19]
	v_mfma_f32_16x16x32_f16 v[12:15], v[176:179], v[224:227], v[12:15]
	v_mfma_f32_16x16x32_f16 v[64:67], v[164:167], v[204:207], v[64:67]
	v_mfma_f32_16x16x32_f16 v[60:63], v[180:183], v[204:207], v[60:63]
	v_mfma_f32_16x16x32_f16 v[48:51], v[164:167], v[212:215], v[48:51]
	v_mfma_f32_16x16x32_f16 v[44:47], v[180:183], v[212:215], v[44:47]
	v_mfma_f32_16x16x32_f16 v[32:35], v[164:167], v[220:223], v[32:35]
	v_mfma_f32_16x16x32_f16 v[28:31], v[180:183], v[220:223], v[28:31]
	v_mfma_f32_16x16x32_f16 v[16:19], v[164:167], v[228:231], v[16:19]
	v_mfma_f32_16x16x32_f16 v[12:15], v[180:183], v[228:231], v[12:15]
	s_setprio 0
	s_setprio 1
	v_mfma_f32_16x16x32_f16 v[56:59], v[184:187], v[200:203], v[56:59]
	v_mfma_f32_16x16x32_f16 v[52:55], v[192:195], v[200:203], v[52:55]
	v_mfma_f32_16x16x32_f16 v[40:43], v[184:187], v[208:211], v[40:43]
	v_mfma_f32_16x16x32_f16 v[36:39], v[192:195], v[208:211], v[36:39]
	v_mfma_f32_16x16x32_f16 v[24:27], v[184:187], v[216:219], v[24:27]
	v_mfma_f32_16x16x32_f16 v[20:23], v[192:195], v[216:219], v[20:23]
	v_mfma_f32_16x16x32_f16 v[8:11], v[184:187], v[224:227], v[8:11]
	v_mfma_f32_16x16x32_f16 v[4:7], v[192:195], v[224:227], v[4:7]
	v_mfma_f32_16x16x32_f16 v[56:59], v[188:191], v[204:207], v[56:59]
	v_mfma_f32_16x16x32_f16 v[52:55], v[196:199], v[204:207], v[52:55]
	v_mfma_f32_16x16x32_f16 v[40:43], v[188:191], v[212:215], v[40:43]
	v_mfma_f32_16x16x32_f16 v[36:39], v[196:199], v[212:215], v[36:39]
	v_mfma_f32_16x16x32_f16 v[24:27], v[188:191], v[220:223], v[24:27]
	v_mfma_f32_16x16x32_f16 v[20:23], v[196:199], v[220:223], v[20:23]
	v_mfma_f32_16x16x32_f16 v[8:11], v[188:191], v[228:231], v[8:11]
	v_mfma_f32_16x16x32_f16 v[4:7], v[196:199], v[228:231], v[4:7]
	s_setprio 0
	s_barrier
	s_add_i32 s2, 0, 0x18000
	s_add_i32 s3, 0, 0x1c000
	v_add_u32_e32 v180, s2, v151
	v_add_u32_e32 v196, s3, v151
	ds_read_b128 v[144:147], v180
	ds_read_b128 v[164:167], v180 offset:1024
	ds_read_b128 v[176:179], v180 offset:2048
	ds_read_b128 v[180:183], v180 offset:3072
	ds_read_b128 v[184:187], v196
	ds_read_b128 v[188:191], v196 offset:1024
	ds_read_b128 v[192:195], v196 offset:2048
	ds_read_b128 v[196:199], v196 offset:3072
	s_add_u32 s56, s56, 0x40000
	s_addc_u32 s57, s57, 0
	s_mov_b32 m0, s58
	ds_read_b128 v[200:203], v153 offset:32768
	ds_read_b128 v[204:207], v153 offset:33792
	ds_read_b128 v[208:211], v153 offset:34816
	ds_read_b128 v[212:215], v153 offset:35840
	ds_read_b128 v[216:219], v153 offset:36864
	ds_read_b128 v[220:223], v153 offset:37888
	ds_read_b128 v[224:227], v153 offset:38912
	ds_read_b128 v[228:231], v153 offset:39936
	global_load_lds_dwordx4 v138, s[56:57]
	s_mov_b32 m0, s59
	s_nop 0
	global_load_lds_dwordx4 v134, s[56:57]
	s_waitcnt vmcnt(8)
	s_waitcnt lgkmcnt(0)
	v_mfma_f32_16x16x32_f16 v[128:131], v[144:147], v[200:203], v[128:131]
	v_mfma_f32_16x16x32_f16 v[124:127], v[176:179], v[200:203], v[124:127]
	v_mfma_f32_16x16x32_f16 v[112:115], v[144:147], v[208:211], v[112:115]
	v_mfma_f32_16x16x32_f16 v[108:111], v[176:179], v[208:211], v[108:111]
	s_barrier
	s_setprio 1
	s_waitcnt lgkmcnt(0)
	v_mfma_f32_16x16x32_f16 v[96:99], v[144:147], v[216:219], v[96:99]
	v_mfma_f32_16x16x32_f16 v[92:95], v[176:179], v[216:219], v[92:95]
	v_mfma_f32_16x16x32_f16 v[80:83], v[144:147], v[224:227], v[80:83]
	v_mfma_f32_16x16x32_f16 v[76:79], v[176:179], v[224:227], v[76:79]
	v_mfma_f32_16x16x32_f16 v[128:131], v[164:167], v[204:207], v[128:131]
	v_mfma_f32_16x16x32_f16 v[124:127], v[180:183], v[204:207], v[124:127]
	v_mfma_f32_16x16x32_f16 v[112:115], v[164:167], v[212:215], v[112:115]
	v_mfma_f32_16x16x32_f16 v[108:111], v[180:183], v[212:215], v[108:111]
	v_mfma_f32_16x16x32_f16 v[96:99], v[164:167], v[220:223], v[96:99]
	v_mfma_f32_16x16x32_f16 v[92:95], v[180:183], v[220:223], v[92:95]
	v_mfma_f32_16x16x32_f16 v[80:83], v[164:167], v[228:231], v[80:83]
	v_mfma_f32_16x16x32_f16 v[76:79], v[180:183], v[228:231], v[76:79]
	s_setprio 0
	s_setprio 1
	v_mfma_f32_16x16x32_f16 v[120:123], v[184:187], v[200:203], v[120:123]
	v_mfma_f32_16x16x32_f16 v[116:119], v[192:195], v[200:203], v[116:119]
	v_mfma_f32_16x16x32_f16 v[104:107], v[184:187], v[208:211], v[104:107]
	v_mfma_f32_16x16x32_f16 v[100:103], v[192:195], v[208:211], v[100:103]
	v_mfma_f32_16x16x32_f16 v[88:91], v[184:187], v[216:219], v[88:91]
	v_mfma_f32_16x16x32_f16 v[84:87], v[192:195], v[216:219], v[84:87]
	v_mfma_f32_16x16x32_f16 v[72:75], v[184:187], v[224:227], v[72:75]
	v_mfma_f32_16x16x32_f16 v[68:71], v[192:195], v[224:227], v[68:71]
	v_mfma_f32_16x16x32_f16 v[120:123], v[188:191], v[204:207], v[120:123]
	v_mfma_f32_16x16x32_f16 v[116:119], v[196:199], v[204:207], v[116:119]
	v_mfma_f32_16x16x32_f16 v[104:107], v[188:191], v[212:215], v[104:107]
	v_mfma_f32_16x16x32_f16 v[100:103], v[196:199], v[212:215], v[100:103]
	v_mfma_f32_16x16x32_f16 v[88:91], v[188:191], v[220:223], v[88:91]
	v_mfma_f32_16x16x32_f16 v[84:87], v[196:199], v[220:223], v[84:87]
	v_mfma_f32_16x16x32_f16 v[72:75], v[188:191], v[228:231], v[72:75]
	v_mfma_f32_16x16x32_f16 v[68:71], v[196:199], v[228:231], v[68:71]
	s_setprio 0
	s_barrier
	s_add_i32 s2, s2, s16
	s_add_u32 s90, s90, 0x80
	s_addc_u32 s91, s91, 0
	s_add_u32 s56, s56, 0xfffc0080
	s_addc_u32 s57, s57, -1
	s_mov_b32 m0, s2
	ds_read_b128 v[200:203], v153 offset:49152
	ds_read_b128 v[204:207], v153 offset:50176
	ds_read_b128 v[208:211], v153 offset:51200
	ds_read_b128 v[212:215], v153 offset:52224
	ds_read_b128 v[216:219], v153 offset:53248
	ds_read_b128 v[220:223], v153 offset:54272
	ds_read_b128 v[224:227], v153 offset:55296
	ds_read_b128 v[228:231], v153 offset:56320
	global_load_lds_dwordx4 v2, s[90:91]
	s_add_i32 m0, s2, 0x2000
	s_add_i32 s2, s3, s16
	global_load_lds_dwordx4 v0, s[90:91]
	s_mov_b32 m0, s2
	s_nop 0
	global_load_lds_dwordx4 v136, s[90:91]
	s_add_i32 m0, s2, 0x2000
	s_nop 0
	global_load_lds_dwordx4 v132, s[90:91]
	s_mov_b32 m0, s60
	s_nop 0
	global_load_lds_dwordx4 v138, s[56:57]
	s_mov_b32 m0, s61
	s_nop 0
	global_load_lds_dwordx4 v134, s[56:57]
	s_waitcnt vmcnt(8)
	s_waitcnt lgkmcnt(0)
	v_mfma_f32_16x16x32_f16 v[64:67], v[144:147], v[200:203], v[64:67]
	v_mfma_f32_16x16x32_f16 v[60:63], v[176:179], v[200:203], v[60:63]
	v_mfma_f32_16x16x32_f16 v[48:51], v[144:147], v[208:211], v[48:51]
	v_mfma_f32_16x16x32_f16 v[44:47], v[176:179], v[208:211], v[44:47]
	s_barrier
	s_setprio 1
	s_waitcnt lgkmcnt(0)
	v_mfma_f32_16x16x32_f16 v[32:35], v[144:147], v[216:219], v[32:35]
	v_mfma_f32_16x16x32_f16 v[28:31], v[176:179], v[216:219], v[28:31]
	v_mfma_f32_16x16x32_f16 v[16:19], v[144:147], v[224:227], v[16:19]
	v_mfma_f32_16x16x32_f16 v[12:15], v[176:179], v[224:227], v[12:15]
	v_mfma_f32_16x16x32_f16 v[64:67], v[164:167], v[204:207], v[64:67]
	v_mfma_f32_16x16x32_f16 v[60:63], v[180:183], v[204:207], v[60:63]
	v_mfma_f32_16x16x32_f16 v[48:51], v[164:167], v[212:215], v[48:51]
	v_mfma_f32_16x16x32_f16 v[44:47], v[180:183], v[212:215], v[44:47]
	v_mfma_f32_16x16x32_f16 v[32:35], v[164:167], v[220:223], v[32:35]
	v_mfma_f32_16x16x32_f16 v[28:31], v[180:183], v[220:223], v[28:31]
	v_mfma_f32_16x16x32_f16 v[16:19], v[164:167], v[228:231], v[16:19]
	v_mfma_f32_16x16x32_f16 v[12:15], v[180:183], v[228:231], v[12:15]
	s_setprio 0
	s_setprio 1
	v_mfma_f32_16x16x32_f16 v[56:59], v[184:187], v[200:203], v[56:59]
	v_mfma_f32_16x16x32_f16 v[52:55], v[192:195], v[200:203], v[52:55]
	v_mfma_f32_16x16x32_f16 v[40:43], v[184:187], v[208:211], v[40:43]
	v_mfma_f32_16x16x32_f16 v[36:39], v[192:195], v[208:211], v[36:39]
	v_mfma_f32_16x16x32_f16 v[24:27], v[184:187], v[216:219], v[24:27]
	v_mfma_f32_16x16x32_f16 v[20:23], v[192:195], v[216:219], v[20:23]
	v_mfma_f32_16x16x32_f16 v[8:11], v[184:187], v[224:227], v[8:11]
	v_mfma_f32_16x16x32_f16 v[4:7], v[192:195], v[224:227], v[4:7]
	v_mfma_f32_16x16x32_f16 v[56:59], v[188:191], v[204:207], v[56:59]
	v_mfma_f32_16x16x32_f16 v[52:55], v[196:199], v[204:207], v[52:55]
	v_mfma_f32_16x16x32_f16 v[40:43], v[188:191], v[212:215], v[40:43]
	v_mfma_f32_16x16x32_f16 v[36:39], v[196:199], v[212:215], v[36:39]
	v_mfma_f32_16x16x32_f16 v[24:27], v[188:191], v[220:223], v[24:27]
	v_mfma_f32_16x16x32_f16 v[20:23], v[196:199], v[220:223], v[20:23]
	v_mfma_f32_16x16x32_f16 v[8:11], v[188:191], v[228:231], v[8:11]
	v_mfma_f32_16x16x32_f16 v[4:7], v[196:199], v[228:231], v[4:7]
	s_setprio 0
	s_barrier
	s_add_i32 s89, s89, 2
	s_add_u32 s6, s6, 0x100
	s_addc_u32 s7, s7, 0
	s_add_u32 s62, s62, 0x100
	s_addc_u32 s88, s88, 0
	s_cmp_gt_u32 s89, 13
	s_cbranch_scc0 .LBB0_202
	s_and_b64 vcc, exec, s[46:47]
	s_cbranch_vccz .LBB0_205
	s_barrier

.LBB0_589:
	ds_read_b128 v[156:159], v152
	ds_read_b128 v[160:163], v152 offset:1024
	ds_read_b128 v[164:167], v152 offset:2048
	ds_read_b128 v[172:175], v152 offset:3072
	ds_read_b128 v[176:179], v153
	ds_read_b128 v[180:183], v153 offset:1024
	ds_read_b128 v[184:187], v153 offset:2048
	ds_read_b128 v[188:191], v153 offset:3072
	s_add_u32 s2, s44, 0xfffc0080
	s_addc_u32 s3, s45, -1
	s_cmp_eq_u32 s54, 12
	s_cselect_b32 s47, s25, s3
	s_cselect_b32 s46, s50, s2
	s_cselect_b32 s57, s19, s53
	s_cselect_b32 s56, s51, s52
	s_add_i32 m0, s14, 0xc000
	ds_read_b128 v[192:195], v154
	ds_read_b128 v[196:199], v154 offset:1024
	ds_read_b128 v[200:203], v154 offset:2048
	ds_read_b128 v[204:207], v154 offset:3072
	ds_read_b128 v[208:211], v154 offset:4096
	ds_read_b128 v[212:215], v154 offset:5120
	ds_read_b128 v[216:219], v154 offset:6144
	ds_read_b128 v[220:223], v154 offset:7168
	global_load_lds_dwordx4 v142, s[44:45]
	s_add_i32 m0, s14, 0xe000
	s_nop 0
	global_load_lds_dwordx4 v144, s[44:45]
	s_waitcnt vmcnt(8)
	s_waitcnt lgkmcnt(0)
	v_mfma_f32_16x16x32_f16 v[124:127], v[156:159], v[192:195], v[124:127]
	v_mfma_f32_16x16x32_f16 v[120:123], v[164:167], v[192:195], v[120:123]
	v_mfma_f32_16x16x32_f16 v[116:119], v[156:159], v[200:203], v[116:119]
	v_mfma_f32_16x16x32_f16 v[108:111], v[164:167], v[200:203], v[108:111]
	s_barrier
	s_setprio 1
	s_waitcnt lgkmcnt(0)
	v_mfma_f32_16x16x32_f16 v[100:103], v[156:159], v[208:211], v[100:103]
	v_mfma_f32_16x16x32_f16 v[92:95], v[164:167], v[208:211], v[92:95]
	v_mfma_f32_16x16x32_f16 v[84:87], v[156:159], v[216:219], v[84:87]
	v_mfma_f32_16x16x32_f16 v[76:79], v[164:167], v[216:219], v[76:79]
	v_mfma_f32_16x16x32_f16 v[124:127], v[160:163], v[196:199], v[124:127]
	v_mfma_f32_16x16x32_f16 v[120:123], v[172:175], v[196:199], v[120:123]
	v_mfma_f32_16x16x32_f16 v[116:119], v[160:163], v[204:207], v[116:119]
	v_mfma_f32_16x16x32_f16 v[108:111], v[172:175], v[204:207], v[108:111]
	v_mfma_f32_16x16x32_f16 v[100:103], v[160:163], v[212:215], v[100:103]
	v_mfma_f32_16x16x32_f16 v[92:95], v[172:175], v[212:215], v[92:95]
	v_mfma_f32_16x16x32_f16 v[84:87], v[160:163], v[220:223], v[84:87]
	v_mfma_f32_16x16x32_f16 v[76:79], v[172:175], v[220:223], v[76:79]
	s_setprio 0
	s_setprio 1
	v_mfma_f32_16x16x32_f16 v[112:115], v[176:179], v[192:195], v[112:115]
	v_mfma_f32_16x16x32_f16 v[104:107], v[184:187], v[192:195], v[104:107]
	v_mfma_f32_16x16x32_f16 v[96:99], v[176:179], v[200:203], v[96:99]
	v_mfma_f32_16x16x32_f16 v[88:91], v[184:187], v[200:203], v[88:91]
	v_mfma_f32_16x16x32_f16 v[80:83], v[176:179], v[208:211], v[80:83]
	v_mfma_f32_16x16x32_f16 v[72:75], v[184:187], v[208:211], v[72:75]
	v_mfma_f32_16x16x32_f16 v[68:71], v[176:179], v[216:219], v[68:71]
	v_mfma_f32_16x16x32_f16 v[64:67], v[184:187], v[216:219], v[64:67]
	v_mfma_f32_16x16x32_f16 v[112:115], v[180:183], v[196:199], v[112:115]
	v_mfma_f32_16x16x32_f16 v[104:107], v[188:191], v[196:199], v[104:107]
	v_mfma_f32_16x16x32_f16 v[96:99], v[180:183], v[204:207], v[96:99]
	v_mfma_f32_16x16x32_f16 v[88:91], v[188:191], v[204:207], v[88:91]
	v_mfma_f32_16x16x32_f16 v[80:83], v[180:183], v[212:215], v[80:83]
	v_mfma_f32_16x16x32_f16 v[72:75], v[188:191], v[212:215], v[72:75]
	v_mfma_f32_16x16x32_f16 v[68:71], v[180:183], v[220:223], v[68:71]
	v_mfma_f32_16x16x32_f16 v[64:67], v[188:191], v[220:223], v[64:67]
	s_setprio 0
	s_barrier
	s_add_i32 s2, s29, s12
	s_mov_b32 m0, s2
	ds_read_b128 v[192:195], v154 offset:16384
	ds_read_b128 v[196:199], v154 offset:17408
	ds_read_b128 v[200:203], v154 offset:18432
	ds_read_b128 v[204:207], v154 offset:19456
	ds_read_b128 v[208:211], v154 offset:20480
	ds_read_b128 v[212:215], v154 offset:21504
	ds_read_b128 v[216:219], v154 offset:22528
	ds_read_b128 v[220:223], v154 offset:23552
	global_load_lds_dwordx4 v134, s[56:57]
	s_add_i32 m0, s2, 0x2000
	s_add_i32 s2, s48, s12
	global_load_lds_dwordx4 v128, s[56:57]
	s_mov_b32 m0, s2
	s_nop 0
	global_load_lds_dwordx4 v136, s[56:57]
	s_add_i32 m0, s2, 0x2000
	s_nop 0
	global_load_lds_dwordx4 v130, s[56:57]
	s_mov_b32 m0, s14
	s_nop 0
	global_load_lds_dwordx4 v138, s[46:47]
	s_mov_b32 m0, s15
	s_nop 0
	global_load_lds_dwordx4 v132, s[46:47]
	s_waitcnt vmcnt(8)
	s_waitcnt lgkmcnt(0)
	v_mfma_f32_16x16x32_f16 v[60:63], v[156:159], v[192:195], v[60:63]
	v_mfma_f32_16x16x32_f16 v[56:59], v[164:167], v[192:195], v[56:59]
	v_mfma_f32_16x16x32_f16 v[52:55], v[156:159], v[200:203], v[52:55]
	v_mfma_f32_16x16x32_f16 v[44:47], v[164:167], v[200:203], v[44:47]
	s_barrier
	s_setprio 1
	s_waitcnt lgkmcnt(0)
	v_mfma_f32_16x16x32_f16 v[36:39], v[156:159], v[208:211], v[36:39]
	v_mfma_f32_16x16x32_f16 v[28:31], v[164:167], v[208:211], v[28:31]
	v_mfma_f32_16x16x32_f16 v[20:23], v[156:159], v[216:219], v[20:23]
	v_mfma_f32_16x16x32_f16 v[12:15], v[164:167], v[216:219], v[12:15]
	v_mfma_f32_16x16x32_f16 v[60:63], v[160:163], v[196:199], v[60:63]
	v_mfma_f32_16x16x32_f16 v[56:59], v[172:175], v[196:199], v[56:59]
	v_mfma_f32_16x16x32_f16 v[52:55], v[160:163], v[204:207], v[52:55]
	v_mfma_f32_16x16x32_f16 v[44:47], v[172:175], v[204:207], v[44:47]
	v_mfma_f32_16x16x32_f16 v[36:39], v[160:163], v[212:215], v[36:39]
	v_mfma_f32_16x16x32_f16 v[28:31], v[172:175], v[212:215], v[28:31]
	v_mfma_f32_16x16x32_f16 v[20:23], v[160:163], v[220:223], v[20:23]
	v_mfma_f32_16x16x32_f16 v[12:15], v[172:175], v[220:223], v[12:15]
	s_setprio 0
	s_setprio 1
	v_mfma_f32_16x16x32_f16 v[48:51], v[176:179], v[192:195], v[48:51]
	v_mfma_f32_16x16x32_f16 v[40:43], v[184:187], v[192:195], v[40:43]
	v_mfma_f32_16x16x32_f16 v[32:35], v[176:179], v[200:203], v[32:35]
	v_mfma_f32_16x16x32_f16 v[24:27], v[184:187], v[200:203], v[24:27]
	v_mfma_f32_16x16x32_f16 v[16:19], v[176:179], v[208:211], v[16:19]
	v_mfma_f32_16x16x32_f16 v[8:11], v[184:187], v[208:211], v[8:11]
	v_mfma_f32_16x16x32_f16 v[4:7], v[176:179], v[216:219], v[4:7]
	v_mfma_f32_16x16x32_f16 v[0:3], v[184:187], v[216:219], v[0:3]
	v_mfma_f32_16x16x32_f16 v[48:51], v[180:183], v[196:199], v[48:51]
	v_mfma_f32_16x16x32_f16 v[40:43], v[188:191], v[196:199], v[40:43]
	v_mfma_f32_16x16x32_f16 v[32:35], v[180:183], v[204:207], v[32:35]
	v_mfma_f32_16x16x32_f16 v[24:27], v[188:191], v[204:207], v[24:27]
	v_mfma_f32_16x16x32_f16 v[16:19], v[180:183], v[212:215], v[16:19]
	v_mfma_f32_16x16x32_f16 v[8:11], v[188:191], v[212:215], v[8:11]
	v_mfma_f32_16x16x32_f16 v[4:7], v[180:183], v[220:223], v[4:7]
	v_mfma_f32_16x16x32_f16 v[0:3], v[188:191], v[220:223], v[0:3]
	s_setprio 0
	s_barrier
	s_add_i32 s2, 0, 0x18000
	s_add_i32 s3, 0, 0x1c000
	v_add_u32_e32 v172, s2, v151
	v_add_u32_e32 v188, s3, v151
	ds_read_b128 v[156:159], v172
	ds_read_b128 v[160:163], v172 offset:1024
	ds_read_b128 v[164:167], v172 offset:2048
	ds_read_b128 v[172:175], v172 offset:3072
	ds_read_b128 v[176:179], v188
	ds_read_b128 v[180:183], v188 offset:1024
	ds_read_b128 v[184:187], v188 offset:2048
	ds_read_b128 v[188:191], v188 offset:3072
	s_add_u32 s46, s46, 0x40000
	s_addc_u32 s47, s47, 0
	s_mov_b32 m0, s16
	ds_read_b128 v[192:195], v154 offset:32768
	ds_read_b128 v[196:199], v154 offset:33792
	ds_read_b128 v[200:203], v154 offset:34816
	ds_read_b128 v[204:207], v154 offset:35840
	ds_read_b128 v[208:211], v154 offset:36864
	ds_read_b128 v[212:215], v154 offset:37888
	ds_read_b128 v[216:219], v154 offset:38912
	ds_read_b128 v[220:223], v154 offset:39936
	global_load_lds_dwordx4 v138, s[46:47]
	s_mov_b32 m0, s17
	s_nop 0
	global_load_lds_dwordx4 v132, s[46:47]
	s_waitcnt vmcnt(8)
	s_waitcnt lgkmcnt(0)
	v_mfma_f32_16x16x32_f16 v[124:127], v[156:159], v[192:195], v[124:127]
	v_mfma_f32_16x16x32_f16 v[120:123], v[164:167], v[192:195], v[120:123]
	v_mfma_f32_16x16x32_f16 v[116:119], v[156:159], v[200:203], v[116:119]
	v_mfma_f32_16x16x32_f16 v[108:111], v[164:167], v[200:203], v[108:111]
	s_barrier
	s_setprio 1
	s_waitcnt lgkmcnt(0)
	v_mfma_f32_16x16x32_f16 v[100:103], v[156:159], v[208:211], v[100:103]
	v_mfma_f32_16x16x32_f16 v[92:95], v[164:167], v[208:211], v[92:95]
	v_mfma_f32_16x16x32_f16 v[84:87], v[156:159], v[216:219], v[84:87]
	v_mfma_f32_16x16x32_f16 v[76:79], v[164:167], v[216:219], v[76:79]
	v_mfma_f32_16x16x32_f16 v[124:127], v[160:163], v[196:199], v[124:127]
	v_mfma_f32_16x16x32_f16 v[120:123], v[172:175], v[196:199], v[120:123]
	v_mfma_f32_16x16x32_f16 v[116:119], v[160:163], v[204:207], v[116:119]
	v_mfma_f32_16x16x32_f16 v[108:111], v[172:175], v[204:207], v[108:111]
	v_mfma_f32_16x16x32_f16 v[100:103], v[160:163], v[212:215], v[100:103]
	v_mfma_f32_16x16x32_f16 v[92:95], v[172:175], v[212:215], v[92:95]
	v_mfma_f32_16x16x32_f16 v[84:87], v[160:163], v[220:223], v[84:87]
	v_mfma_f32_16x16x32_f16 v[76:79], v[172:175], v[220:223], v[76:79]
	s_setprio 0
	s_setprio 1
	v_mfma_f32_16x16x32_f16 v[112:115], v[176:179], v[192:195], v[112:115]
	v_mfma_f32_16x16x32_f16 v[104:107], v[184:187], v[192:195], v[104:107]
	v_mfma_f32_16x16x32_f16 v[96:99], v[176:179], v[200:203], v[96:99]
	v_mfma_f32_16x16x32_f16 v[88:91], v[184:187], v[200:203], v[88:91]
	v_mfma_f32_16x16x32_f16 v[80:83], v[176:179], v[208:211], v[80:83]
	v_mfma_f32_16x16x32_f16 v[72:75], v[184:187], v[208:211], v[72:75]
	v_mfma_f32_16x16x32_f16 v[68:71], v[176:179], v[216:219], v[68:71]
	v_mfma_f32_16x16x32_f16 v[64:67], v[184:187], v[216:219], v[64:67]
	v_mfma_f32_16x16x32_f16 v[112:115], v[180:183], v[196:199], v[112:115]
	v_mfma_f32_16x16x32_f16 v[104:107], v[188:191], v[196:199], v[104:107]
	v_mfma_f32_16x16x32_f16 v[96:99], v[180:183], v[204:207], v[96:99]
	v_mfma_f32_16x16x32_f16 v[88:91], v[188:191], v[204:207], v[88:91]
	v_mfma_f32_16x16x32_f16 v[80:83], v[180:183], v[212:215], v[80:83]
	v_mfma_f32_16x16x32_f16 v[72:75], v[188:191], v[212:215], v[72:75]
	v_mfma_f32_16x16x32_f16 v[68:71], v[180:183], v[220:223], v[68:71]
	v_mfma_f32_16x16x32_f16 v[64:67], v[188:191], v[220:223], v[64:67]
	s_setprio 0
	s_barrier
	s_add_i32 s2, s2, s12
	s_add_u32 s56, s56, 0x80
	s_addc_u32 s57, s57, 0
	s_add_u32 s46, s46, 0xfffc0080
	s_addc_u32 s47, s47, -1
	s_mov_b32 m0, s2
	ds_read_b128 v[192:195], v154 offset:49152
	ds_read_b128 v[196:199], v154 offset:50176
	ds_read_b128 v[200:203], v154 offset:51200
	ds_read_b128 v[204:207], v154 offset:52224
	ds_read_b128 v[208:211], v154 offset:53248
	ds_read_b128 v[212:215], v154 offset:54272
	ds_read_b128 v[216:219], v154 offset:55296
	ds_read_b128 v[220:223], v154 offset:56320
	global_load_lds_dwordx4 v134, s[56:57]
	s_add_i32 m0, s2, 0x2000
	s_add_i32 s2, s3, s12
	global_load_lds_dwordx4 v128, s[56:57]
	s_mov_b32 m0, s2
	s_nop 0
	global_load_lds_dwordx4 v136, s[56:57]
	s_add_i32 m0, s2, 0x2000
	s_nop 0
	global_load_lds_dwordx4 v130, s[56:57]
	s_mov_b32 m0, s20
	s_nop 0
	global_load_lds_dwordx4 v138, s[46:47]
	s_mov_b32 m0, s21
	s_nop 0
	global_load_lds_dwordx4 v132, s[46:47]
	s_waitcnt vmcnt(8)
	s_waitcnt lgkmcnt(0)
	v_mfma_f32_16x16x32_f16 v[60:63], v[156:159], v[192:195], v[60:63]
	v_mfma_f32_16x16x32_f16 v[56:59], v[164:167], v[192:195], v[56:59]
	v_mfma_f32_16x16x32_f16 v[52:55], v[156:159], v[200:203], v[52:55]
	v_mfma_f32_16x16x32_f16 v[44:47], v[164:167], v[200:203], v[44:47]
	s_barrier
	s_setprio 1
	s_waitcnt lgkmcnt(0)
	v_mfma_f32_16x16x32_f16 v[36:39], v[156:159], v[208:211], v[36:39]
	v_mfma_f32_16x16x32_f16 v[28:31], v[164:167], v[208:211], v[28:31]
	v_mfma_f32_16x16x32_f16 v[20:23], v[156:159], v[216:219], v[20:23]
	v_mfma_f32_16x16x32_f16 v[12:15], v[164:167], v[216:219], v[12:15]
	v_mfma_f32_16x16x32_f16 v[60:63], v[160:163], v[196:199], v[60:63]
	v_mfma_f32_16x16x32_f16 v[56:59], v[172:175], v[196:199], v[56:59]
	v_mfma_f32_16x16x32_f16 v[52:55], v[160:163], v[204:207], v[52:55]
	v_mfma_f32_16x16x32_f16 v[44:47], v[172:175], v[204:207], v[44:47]
	v_mfma_f32_16x16x32_f16 v[36:39], v[160:163], v[212:215], v[36:39]
	v_mfma_f32_16x16x32_f16 v[28:31], v[172:175], v[212:215], v[28:31]
	v_mfma_f32_16x16x32_f16 v[20:23], v[160:163], v[220:223], v[20:23]
	v_mfma_f32_16x16x32_f16 v[12:15], v[172:175], v[220:223], v[12:15]
	s_setprio 0
	s_setprio 1
	v_mfma_f32_16x16x32_f16 v[48:51], v[176:179], v[192:195], v[48:51]
	v_mfma_f32_16x16x32_f16 v[40:43], v[184:187], v[192:195], v[40:43]
	v_mfma_f32_16x16x32_f16 v[32:35], v[176:179], v[200:203], v[32:35]
	v_mfma_f32_16x16x32_f16 v[24:27], v[184:187], v[200:203], v[24:27]
	v_mfma_f32_16x16x32_f16 v[16:19], v[176:179], v[208:211], v[16:19]
	v_mfma_f32_16x16x32_f16 v[8:11], v[184:187], v[208:211], v[8:11]
	v_mfma_f32_16x16x32_f16 v[4:7], v[176:179], v[216:219], v[4:7]
	v_mfma_f32_16x16x32_f16 v[0:3], v[184:187], v[216:219], v[0:3]
	v_mfma_f32_16x16x32_f16 v[48:51], v[180:183], v[196:199], v[48:51]
	v_mfma_f32_16x16x32_f16 v[40:43], v[188:191], v[196:199], v[40:43]
	v_mfma_f32_16x16x32_f16 v[32:35], v[180:183], v[204:207], v[32:35]
	v_mfma_f32_16x16x32_f16 v[24:27], v[188:191], v[204:207], v[24:27]
	v_mfma_f32_16x16x32_f16 v[16:19], v[180:183], v[212:215], v[16:19]
	v_mfma_f32_16x16x32_f16 v[8:11], v[188:191], v[212:215], v[8:11]
	v_mfma_f32_16x16x32_f16 v[4:7], v[180:183], v[220:223], v[4:7]
	v_mfma_f32_16x16x32_f16 v[0:3], v[188:191], v[220:223], v[0:3]
	s_setprio 0
	s_barrier
	s_add_i32 s54, s54, 2
	s_add_u32 s44, s44, 0x100
	s_addc_u32 s45, s45, 0
	s_add_u32 s52, s52, 0x100
	s_addc_u32 s53, s53, 0
	s_cmp_gt_u32 s54, 13
	s_cbranch_scc0 .LBB0_589
	s_and_b64 vcc, exec, s[8:9]
	s_cbranch_vccz .LBB0_592
	s_barrier

.LBB0_609:
	ds_read_b128 v[156:159], v152
	ds_read_b128 v[160:163], v152 offset:1024
	ds_read_b128 v[164:167], v152 offset:2048
	ds_read_b128 v[172:175], v152 offset:3072
	ds_read_b128 v[176:179], v153
	ds_read_b128 v[180:183], v153 offset:1024
	ds_read_b128 v[184:187], v153 offset:2048
	ds_read_b128 v[188:191], v153 offset:3072
	s_add_u32 s2, s44, 0xfffc0080
	s_addc_u32 s3, s45, -1
	s_cmp_eq_u32 s53, 12
	s_cselect_b32 s47, s27, s3
	s_cselect_b32 s46, s49, s2
	s_cselect_b32 s55, s25, s52
	s_cselect_b32 s54, s50, s51
	s_add_i32 m0, s15, 0xc000
	ds_read_b128 v[192:195], v154
	ds_read_b128 v[196:199], v154 offset:1024
	ds_read_b128 v[200:203], v154 offset:2048
	ds_read_b128 v[204:207], v154 offset:3072
	ds_read_b128 v[208:211], v154 offset:4096
	ds_read_b128 v[212:215], v154 offset:5120
	ds_read_b128 v[216:219], v154 offset:6144
	ds_read_b128 v[220:223], v154 offset:7168
	global_load_lds_dwordx4 v142, s[44:45]
	s_add_i32 m0, s15, 0xe000
	s_nop 0
	global_load_lds_dwordx4 v144, s[44:45]
	s_waitcnt vmcnt(8)
	s_waitcnt lgkmcnt(0)
	v_mfma_f32_16x16x32_f16 v[124:127], v[156:159], v[192:195], v[124:127]
	v_mfma_f32_16x16x32_f16 v[120:123], v[164:167], v[192:195], v[120:123]
	v_mfma_f32_16x16x32_f16 v[116:119], v[156:159], v[200:203], v[116:119]
	v_mfma_f32_16x16x32_f16 v[112:115], v[164:167], v[200:203], v[112:115]
	s_barrier
	s_setprio 1
	s_waitcnt lgkmcnt(0)
	v_mfma_f32_16x16x32_f16 v[100:103], v[156:159], v[208:211], v[100:103]
	v_mfma_f32_16x16x32_f16 v[96:99], v[164:167], v[208:211], v[96:99]
	v_mfma_f32_16x16x32_f16 v[84:87], v[156:159], v[216:219], v[84:87]
	v_mfma_f32_16x16x32_f16 v[80:83], v[164:167], v[216:219], v[80:83]
	v_mfma_f32_16x16x32_f16 v[124:127], v[160:163], v[196:199], v[124:127]
	v_mfma_f32_16x16x32_f16 v[120:123], v[172:175], v[196:199], v[120:123]
	v_mfma_f32_16x16x32_f16 v[116:119], v[160:163], v[204:207], v[116:119]
	v_mfma_f32_16x16x32_f16 v[112:115], v[172:175], v[204:207], v[112:115]
	v_mfma_f32_16x16x32_f16 v[100:103], v[160:163], v[212:215], v[100:103]
	v_mfma_f32_16x16x32_f16 v[96:99], v[172:175], v[212:215], v[96:99]
	v_mfma_f32_16x16x32_f16 v[84:87], v[160:163], v[220:223], v[84:87]
	v_mfma_f32_16x16x32_f16 v[80:83], v[172:175], v[220:223], v[80:83]
	s_setprio 0
	s_setprio 1
	v_mfma_f32_16x16x32_f16 v[108:111], v[176:179], v[192:195], v[108:111]
	v_mfma_f32_16x16x32_f16 v[104:107], v[184:187], v[192:195], v[104:107]
	v_mfma_f32_16x16x32_f16 v[92:95], v[176:179], v[200:203], v[92:95]
	v_mfma_f32_16x16x32_f16 v[88:91], v[184:187], v[200:203], v[88:91]
	v_mfma_f32_16x16x32_f16 v[76:79], v[176:179], v[208:211], v[76:79]
	v_mfma_f32_16x16x32_f16 v[72:75], v[184:187], v[208:211], v[72:75]
	v_mfma_f32_16x16x32_f16 v[68:71], v[176:179], v[216:219], v[68:71]
	v_mfma_f32_16x16x32_f16 v[64:67], v[184:187], v[216:219], v[64:67]
	v_mfma_f32_16x16x32_f16 v[108:111], v[180:183], v[196:199], v[108:111]
	v_mfma_f32_16x16x32_f16 v[104:107], v[188:191], v[196:199], v[104:107]
	v_mfma_f32_16x16x32_f16 v[92:95], v[180:183], v[204:207], v[92:95]
	v_mfma_f32_16x16x32_f16 v[88:91], v[188:191], v[204:207], v[88:91]
	v_mfma_f32_16x16x32_f16 v[76:79], v[180:183], v[212:215], v[76:79]
	v_mfma_f32_16x16x32_f16 v[72:75], v[188:191], v[212:215], v[72:75]
	v_mfma_f32_16x16x32_f16 v[68:71], v[180:183], v[220:223], v[68:71]
	v_mfma_f32_16x16x32_f16 v[64:67], v[188:191], v[220:223], v[64:67]
	s_setprio 0
	s_barrier
	s_add_i32 s2, s21, s14
	s_mov_b32 m0, s2
	ds_read_b128 v[192:195], v154 offset:16384
	ds_read_b128 v[196:199], v154 offset:17408
	ds_read_b128 v[200:203], v154 offset:18432
	ds_read_b128 v[204:207], v154 offset:19456
	ds_read_b128 v[208:211], v154 offset:20480
	ds_read_b128 v[212:215], v154 offset:21504
	ds_read_b128 v[216:219], v154 offset:22528
	ds_read_b128 v[220:223], v154 offset:23552
	global_load_lds_dwordx4 v134, s[54:55]
	s_add_i32 m0, s2, 0x2000
	s_add_i32 s2, s28, s14
	global_load_lds_dwordx4 v128, s[54:55]
	s_mov_b32 m0, s2
	s_nop 0
	global_load_lds_dwordx4 v136, s[54:55]
	s_add_i32 m0, s2, 0x2000
	s_nop 0
	global_load_lds_dwordx4 v130, s[54:55]
	s_mov_b32 m0, s15
	s_nop 0
	global_load_lds_dwordx4 v138, s[46:47]
	s_mov_b32 m0, s16
	s_nop 0
	global_load_lds_dwordx4 v132, s[46:47]
	s_waitcnt vmcnt(8)
	s_waitcnt lgkmcnt(0)
	v_mfma_f32_16x16x32_f16 v[60:63], v[156:159], v[192:195], v[60:63]
	v_mfma_f32_16x16x32_f16 v[56:59], v[164:167], v[192:195], v[56:59]
	v_mfma_f32_16x16x32_f16 v[52:55], v[156:159], v[200:203], v[52:55]
	v_mfma_f32_16x16x32_f16 v[48:51], v[164:167], v[200:203], v[48:51]
	s_barrier
	s_setprio 1
	s_waitcnt lgkmcnt(0)
	v_mfma_f32_16x16x32_f16 v[36:39], v[156:159], v[208:211], v[36:39]
	v_mfma_f32_16x16x32_f16 v[32:35], v[164:167], v[208:211], v[32:35]
	v_mfma_f32_16x16x32_f16 v[20:23], v[156:159], v[216:219], v[20:23]
	v_mfma_f32_16x16x32_f16 v[16:19], v[164:167], v[216:219], v[16:19]
	v_mfma_f32_16x16x32_f16 v[60:63], v[160:163], v[196:199], v[60:63]
	v_mfma_f32_16x16x32_f16 v[56:59], v[172:175], v[196:199], v[56:59]
	v_mfma_f32_16x16x32_f16 v[52:55], v[160:163], v[204:207], v[52:55]
	v_mfma_f32_16x16x32_f16 v[48:51], v[172:175], v[204:207], v[48:51]
	v_mfma_f32_16x16x32_f16 v[36:39], v[160:163], v[212:215], v[36:39]
	v_mfma_f32_16x16x32_f16 v[32:35], v[172:175], v[212:215], v[32:35]
	v_mfma_f32_16x16x32_f16 v[20:23], v[160:163], v[220:223], v[20:23]
	v_mfma_f32_16x16x32_f16 v[16:19], v[172:175], v[220:223], v[16:19]
	s_setprio 0
	s_setprio 1
	v_mfma_f32_16x16x32_f16 v[44:47], v[176:179], v[192:195], v[44:47]
	v_mfma_f32_16x16x32_f16 v[40:43], v[184:187], v[192:195], v[40:43]
	v_mfma_f32_16x16x32_f16 v[28:31], v[176:179], v[200:203], v[28:31]
	v_mfma_f32_16x16x32_f16 v[24:27], v[184:187], v[200:203], v[24:27]
	v_mfma_f32_16x16x32_f16 v[12:15], v[176:179], v[208:211], v[12:15]
	v_mfma_f32_16x16x32_f16 v[8:11], v[184:187], v[208:211], v[8:11]
	v_mfma_f32_16x16x32_f16 v[4:7], v[176:179], v[216:219], v[4:7]
	v_mfma_f32_16x16x32_f16 v[0:3], v[184:187], v[216:219], v[0:3]
	v_mfma_f32_16x16x32_f16 v[44:47], v[180:183], v[196:199], v[44:47]
	v_mfma_f32_16x16x32_f16 v[40:43], v[188:191], v[196:199], v[40:43]
	v_mfma_f32_16x16x32_f16 v[28:31], v[180:183], v[204:207], v[28:31]
	v_mfma_f32_16x16x32_f16 v[24:27], v[188:191], v[204:207], v[24:27]
	v_mfma_f32_16x16x32_f16 v[12:15], v[180:183], v[212:215], v[12:15]
	v_mfma_f32_16x16x32_f16 v[8:11], v[188:191], v[212:215], v[8:11]
	v_mfma_f32_16x16x32_f16 v[4:7], v[180:183], v[220:223], v[4:7]
	v_mfma_f32_16x16x32_f16 v[0:3], v[188:191], v[220:223], v[0:3]
	s_setprio 0
	s_barrier
	s_add_i32 s2, 0, 0x18000
	v_add_u32_e32 v155, s2, v151
	s_add_i32 s3, 0, 0x1c000
	ds_read_b128 v[156:159], v155
	ds_read_b128 v[160:163], v155 offset:1024
	ds_read_b128 v[164:167], v155 offset:2048
	ds_read_b128 v[172:175], v155 offset:3072
	v_add_u32_e32 v155, s3, v151
	ds_read_b128 v[176:179], v155
	ds_read_b128 v[180:183], v155 offset:1024
	ds_read_b128 v[184:187], v155 offset:2048
	ds_read_b128 v[188:191], v155 offset:3072
	s_add_u32 s46, s46, 0x40000
	s_addc_u32 s47, s47, 0
	s_mov_b32 m0, s17
	ds_read_b128 v[192:195], v154 offset:32768
	ds_read_b128 v[196:199], v154 offset:33792
	ds_read_b128 v[200:203], v154 offset:34816
	ds_read_b128 v[204:207], v154 offset:35840
	ds_read_b128 v[208:211], v154 offset:36864
	ds_read_b128 v[212:215], v154 offset:37888
	ds_read_b128 v[216:219], v154 offset:38912
	ds_read_b128 v[220:223], v154 offset:39936
	global_load_lds_dwordx4 v138, s[46:47]
	s_mov_b32 m0, s18
	s_nop 0
	global_load_lds_dwordx4 v132, s[46:47]
	s_waitcnt vmcnt(8)
	s_waitcnt lgkmcnt(0)
	v_mfma_f32_16x16x32_f16 v[124:127], v[156:159], v[192:195], v[124:127]
	v_mfma_f32_16x16x32_f16 v[120:123], v[164:167], v[192:195], v[120:123]
	v_mfma_f32_16x16x32_f16 v[116:119], v[156:159], v[200:203], v[116:119]
	v_mfma_f32_16x16x32_f16 v[112:115], v[164:167], v[200:203], v[112:115]
	s_barrier
	s_setprio 1
	s_waitcnt lgkmcnt(0)
	v_mfma_f32_16x16x32_f16 v[100:103], v[156:159], v[208:211], v[100:103]
	v_mfma_f32_16x16x32_f16 v[96:99], v[164:167], v[208:211], v[96:99]
	v_mfma_f32_16x16x32_f16 v[84:87], v[156:159], v[216:219], v[84:87]
	v_mfma_f32_16x16x32_f16 v[80:83], v[164:167], v[216:219], v[80:83]
	v_mfma_f32_16x16x32_f16 v[124:127], v[160:163], v[196:199], v[124:127]
	v_mfma_f32_16x16x32_f16 v[120:123], v[172:175], v[196:199], v[120:123]
	v_mfma_f32_16x16x32_f16 v[116:119], v[160:163], v[204:207], v[116:119]
	v_mfma_f32_16x16x32_f16 v[112:115], v[172:175], v[204:207], v[112:115]
	v_mfma_f32_16x16x32_f16 v[100:103], v[160:163], v[212:215], v[100:103]
	v_mfma_f32_16x16x32_f16 v[96:99], v[172:175], v[212:215], v[96:99]
	v_mfma_f32_16x16x32_f16 v[84:87], v[160:163], v[220:223], v[84:87]
	v_mfma_f32_16x16x32_f16 v[80:83], v[172:175], v[220:223], v[80:83]
	s_setprio 0
	s_setprio 1
	v_mfma_f32_16x16x32_f16 v[108:111], v[176:179], v[192:195], v[108:111]
	v_mfma_f32_16x16x32_f16 v[104:107], v[184:187], v[192:195], v[104:107]
	v_mfma_f32_16x16x32_f16 v[92:95], v[176:179], v[200:203], v[92:95]
	v_mfma_f32_16x16x32_f16 v[88:91], v[184:187], v[200:203], v[88:91]
	v_mfma_f32_16x16x32_f16 v[76:79], v[176:179], v[208:211], v[76:79]
	v_mfma_f32_16x16x32_f16 v[72:75], v[184:187], v[208:211], v[72:75]
	v_mfma_f32_16x16x32_f16 v[68:71], v[176:179], v[216:219], v[68:71]
	v_mfma_f32_16x16x32_f16 v[64:67], v[184:187], v[216:219], v[64:67]
	v_mfma_f32_16x16x32_f16 v[108:111], v[180:183], v[196:199], v[108:111]
	v_mfma_f32_16x16x32_f16 v[104:107], v[188:191], v[196:199], v[104:107]
	v_mfma_f32_16x16x32_f16 v[92:95], v[180:183], v[204:207], v[92:95]
	v_mfma_f32_16x16x32_f16 v[88:91], v[188:191], v[204:207], v[88:91]
	v_mfma_f32_16x16x32_f16 v[76:79], v[180:183], v[212:215], v[76:79]
	v_mfma_f32_16x16x32_f16 v[72:75], v[188:191], v[212:215], v[72:75]
	v_mfma_f32_16x16x32_f16 v[68:71], v[180:183], v[220:223], v[68:71]
	v_mfma_f32_16x16x32_f16 v[64:67], v[188:191], v[220:223], v[64:67]
	s_setprio 0
	s_barrier
	s_add_i32 s2, s2, s14
	s_add_u32 s54, s54, 0x80
	s_addc_u32 s55, s55, 0
	s_add_u32 s46, s46, 0xfffc0080
	s_addc_u32 s47, s47, -1
	s_mov_b32 m0, s2
	ds_read_b128 v[192:195], v154 offset:49152
	ds_read_b128 v[196:199], v154 offset:50176
	ds_read_b128 v[200:203], v154 offset:51200
	ds_read_b128 v[204:207], v154 offset:52224
	ds_read_b128 v[208:211], v154 offset:53248
	ds_read_b128 v[212:215], v154 offset:54272
	ds_read_b128 v[216:219], v154 offset:55296
	ds_read_b128 v[220:223], v154 offset:56320
	global_load_lds_dwordx4 v134, s[54:55]
	s_add_i32 m0, s2, 0x2000
	s_add_i32 s2, s3, s14
	global_load_lds_dwordx4 v128, s[54:55]
	s_mov_b32 m0, s2
	s_nop 0
	global_load_lds_dwordx4 v136, s[54:55]
	s_add_i32 m0, s2, 0x2000
	s_nop 0
	global_load_lds_dwordx4 v130, s[54:55]
	s_mov_b32 m0, s19
	s_nop 0
	global_load_lds_dwordx4 v138, s[46:47]
	s_mov_b32 m0, s20
	s_nop 0
	global_load_lds_dwordx4 v132, s[46:47]
	s_waitcnt vmcnt(8)
	s_waitcnt lgkmcnt(0)
	v_mfma_f32_16x16x32_f16 v[60:63], v[156:159], v[192:195], v[60:63]
	v_mfma_f32_16x16x32_f16 v[56:59], v[164:167], v[192:195], v[56:59]
	v_mfma_f32_16x16x32_f16 v[52:55], v[156:159], v[200:203], v[52:55]
	v_mfma_f32_16x16x32_f16 v[48:51], v[164:167], v[200:203], v[48:51]
	s_barrier
	s_setprio 1
	s_waitcnt lgkmcnt(0)
	v_mfma_f32_16x16x32_f16 v[36:39], v[156:159], v[208:211], v[36:39]
	v_mfma_f32_16x16x32_f16 v[32:35], v[164:167], v[208:211], v[32:35]
	v_mfma_f32_16x16x32_f16 v[20:23], v[156:159], v[216:219], v[20:23]
	v_mfma_f32_16x16x32_f16 v[16:19], v[164:167], v[216:219], v[16:19]
	v_mfma_f32_16x16x32_f16 v[60:63], v[160:163], v[196:199], v[60:63]
	v_mfma_f32_16x16x32_f16 v[56:59], v[172:175], v[196:199], v[56:59]
	v_mfma_f32_16x16x32_f16 v[52:55], v[160:163], v[204:207], v[52:55]
	v_mfma_f32_16x16x32_f16 v[48:51], v[172:175], v[204:207], v[48:51]
	v_mfma_f32_16x16x32_f16 v[36:39], v[160:163], v[212:215], v[36:39]
	v_mfma_f32_16x16x32_f16 v[32:35], v[172:175], v[212:215], v[32:35]
	v_mfma_f32_16x16x32_f16 v[20:23], v[160:163], v[220:223], v[20:23]
	v_mfma_f32_16x16x32_f16 v[16:19], v[172:175], v[220:223], v[16:19]
	s_setprio 0
	s_setprio 1
	v_mfma_f32_16x16x32_f16 v[44:47], v[176:179], v[192:195], v[44:47]
	v_mfma_f32_16x16x32_f16 v[40:43], v[184:187], v[192:195], v[40:43]
	v_mfma_f32_16x16x32_f16 v[28:31], v[176:179], v[200:203], v[28:31]
	v_mfma_f32_16x16x32_f16 v[24:27], v[184:187], v[200:203], v[24:27]
	v_mfma_f32_16x16x32_f16 v[12:15], v[176:179], v[208:211], v[12:15]
	v_mfma_f32_16x16x32_f16 v[8:11], v[184:187], v[208:211], v[8:11]
	v_mfma_f32_16x16x32_f16 v[4:7], v[176:179], v[216:219], v[4:7]
	v_mfma_f32_16x16x32_f16 v[0:3], v[184:187], v[216:219], v[0:3]
	v_mfma_f32_16x16x32_f16 v[44:47], v[180:183], v[196:199], v[44:47]
	v_mfma_f32_16x16x32_f16 v[40:43], v[188:191], v[196:199], v[40:43]
	v_mfma_f32_16x16x32_f16 v[28:31], v[180:183], v[204:207], v[28:31]
	v_mfma_f32_16x16x32_f16 v[24:27], v[188:191], v[204:207], v[24:27]
	v_mfma_f32_16x16x32_f16 v[12:15], v[180:183], v[212:215], v[12:15]
	v_mfma_f32_16x16x32_f16 v[8:11], v[188:191], v[212:215], v[8:11]
	v_mfma_f32_16x16x32_f16 v[4:7], v[180:183], v[220:223], v[4:7]
	v_mfma_f32_16x16x32_f16 v[0:3], v[188:191], v[220:223], v[0:3]
	s_setprio 0
	s_barrier
	s_add_i32 s53, s53, 2
	s_add_u32 s44, s44, 0x100
	s_addc_u32 s45, s45, 0
	s_add_u32 s51, s51, 0x100
	s_addc_u32 s52, s52, 0
	s_cmp_gt_u32 s53, 13
	s_cbranch_scc0 .LBB0_609
	s_and_b64 vcc, exec, s[22:23]
	s_cbranch_vccz .LBB0_612
	s_barrier

.LBB0_629:
	ds_read_b128 v[156:159], v152
	ds_read_b128 v[160:163], v152 offset:1024
	ds_read_b128 v[164:167], v152 offset:2048
	ds_read_b128 v[172:175], v152 offset:3072
	ds_read_b128 v[176:179], v153
	ds_read_b128 v[180:183], v153 offset:1024
	ds_read_b128 v[184:187], v153 offset:2048
	ds_read_b128 v[188:191], v153 offset:3072
	s_add_u32 s2, s48, 0xfffc0080
	s_addc_u32 s3, s49, -1
	s_cmp_eq_u32 s55, 12
	s_cselect_b32 s51, s27, s3
	s_cselect_b32 s50, s35, s2
	s_cselect_b32 s57, s31, s54
	s_cselect_b32 s56, s52, s53
	s_add_i32 m0, s15, 0xc000
	ds_read_b128 v[192:195], v154
	ds_read_b128 v[196:199], v154 offset:1024
	ds_read_b128 v[200:203], v154 offset:2048
	ds_read_b128 v[204:207], v154 offset:3072
	ds_read_b128 v[208:211], v154 offset:4096
	ds_read_b128 v[212:215], v154 offset:5120
	ds_read_b128 v[216:219], v154 offset:6144
	ds_read_b128 v[220:223], v154 offset:7168
	global_load_lds_dwordx4 v142, s[48:49]
	s_add_i32 m0, s15, 0xe000
	s_nop 0
	global_load_lds_dwordx4 v144, s[48:49]
	s_waitcnt vmcnt(8)
	s_waitcnt lgkmcnt(0)
	v_mfma_f32_16x16x32_f16 v[124:127], v[156:159], v[192:195], v[124:127]
	v_mfma_f32_16x16x32_f16 v[120:123], v[164:167], v[192:195], v[120:123]
	v_mfma_f32_16x16x32_f16 v[116:119], v[156:159], v[200:203], v[116:119]
	v_mfma_f32_16x16x32_f16 v[108:111], v[164:167], v[200:203], v[108:111]
	s_barrier
	s_setprio 1
	s_waitcnt lgkmcnt(0)
	v_mfma_f32_16x16x32_f16 v[100:103], v[156:159], v[208:211], v[100:103]
	v_mfma_f32_16x16x32_f16 v[92:95], v[164:167], v[208:211], v[92:95]
	v_mfma_f32_16x16x32_f16 v[84:87], v[156:159], v[216:219], v[84:87]
	v_mfma_f32_16x16x32_f16 v[76:79], v[164:167], v[216:219], v[76:79]
	v_mfma_f32_16x16x32_f16 v[124:127], v[160:163], v[196:199], v[124:127]
	v_mfma_f32_16x16x32_f16 v[120:123], v[172:175], v[196:199], v[120:123]
	v_mfma_f32_16x16x32_f16 v[116:119], v[160:163], v[204:207], v[116:119]
	v_mfma_f32_16x16x32_f16 v[108:111], v[172:175], v[204:207], v[108:111]
	v_mfma_f32_16x16x32_f16 v[100:103], v[160:163], v[212:215], v[100:103]
	v_mfma_f32_16x16x32_f16 v[92:95], v[172:175], v[212:215], v[92:95]
	v_mfma_f32_16x16x32_f16 v[84:87], v[160:163], v[220:223], v[84:87]
	v_mfma_f32_16x16x32_f16 v[76:79], v[172:175], v[220:223], v[76:79]
	s_setprio 0
	s_setprio 1
	v_mfma_f32_16x16x32_f16 v[112:115], v[176:179], v[192:195], v[112:115]
	v_mfma_f32_16x16x32_f16 v[104:107], v[184:187], v[192:195], v[104:107]
	v_mfma_f32_16x16x32_f16 v[96:99], v[176:179], v[200:203], v[96:99]
	v_mfma_f32_16x16x32_f16 v[88:91], v[184:187], v[200:203], v[88:91]
	v_mfma_f32_16x16x32_f16 v[80:83], v[176:179], v[208:211], v[80:83]
	v_mfma_f32_16x16x32_f16 v[72:75], v[184:187], v[208:211], v[72:75]
	v_mfma_f32_16x16x32_f16 v[68:71], v[176:179], v[216:219], v[68:71]
	v_mfma_f32_16x16x32_f16 v[64:67], v[184:187], v[216:219], v[64:67]
	v_mfma_f32_16x16x32_f16 v[112:115], v[180:183], v[196:199], v[112:115]
	v_mfma_f32_16x16x32_f16 v[104:107], v[188:191], v[196:199], v[104:107]
	v_mfma_f32_16x16x32_f16 v[96:99], v[180:183], v[204:207], v[96:99]
	v_mfma_f32_16x16x32_f16 v[88:91], v[188:191], v[204:207], v[88:91]
	v_mfma_f32_16x16x32_f16 v[80:83], v[180:183], v[212:215], v[80:83]
	v_mfma_f32_16x16x32_f16 v[72:75], v[188:191], v[212:215], v[72:75]
	v_mfma_f32_16x16x32_f16 v[68:71], v[180:183], v[220:223], v[68:71]
	v_mfma_f32_16x16x32_f16 v[64:67], v[188:191], v[220:223], v[64:67]
	s_setprio 0
	s_barrier
	s_add_i32 s2, s21, s14
	s_mov_b32 m0, s2
	ds_read_b128 v[192:195], v154 offset:16384
	ds_read_b128 v[196:199], v154 offset:17408
	ds_read_b128 v[200:203], v154 offset:18432
	ds_read_b128 v[204:207], v154 offset:19456
	ds_read_b128 v[208:211], v154 offset:20480
	ds_read_b128 v[212:215], v154 offset:21504
	ds_read_b128 v[216:219], v154 offset:22528
	ds_read_b128 v[220:223], v154 offset:23552
	global_load_lds_dwordx4 v136, s[56:57]
	s_add_i32 m0, s2, 0x2000
	s_add_i32 s2, s28, s14
	global_load_lds_dwordx4 v130, s[56:57]
	s_mov_b32 m0, s2
	s_nop 0
	global_load_lds_dwordx4 v134, s[56:57]
	s_add_i32 m0, s2, 0x2000
	s_nop 0
	global_load_lds_dwordx4 v128, s[56:57]
	s_mov_b32 m0, s15
	s_nop 0
	global_load_lds_dwordx4 v138, s[50:51]
	s_mov_b32 m0, s16
	s_nop 0
	global_load_lds_dwordx4 v132, s[50:51]
	s_waitcnt vmcnt(8)
	s_waitcnt lgkmcnt(0)
	v_mfma_f32_16x16x32_f16 v[60:63], v[156:159], v[192:195], v[60:63]
	v_mfma_f32_16x16x32_f16 v[56:59], v[164:167], v[192:195], v[56:59]
	v_mfma_f32_16x16x32_f16 v[52:55], v[156:159], v[200:203], v[52:55]
	v_mfma_f32_16x16x32_f16 v[48:51], v[164:167], v[200:203], v[48:51]
	s_barrier
	s_setprio 1
	s_waitcnt lgkmcnt(0)
	v_mfma_f32_16x16x32_f16 v[36:39], v[156:159], v[208:211], v[36:39]
	v_mfma_f32_16x16x32_f16 v[32:35], v[164:167], v[208:211], v[32:35]
	v_mfma_f32_16x16x32_f16 v[20:23], v[156:159], v[216:219], v[20:23]
	v_mfma_f32_16x16x32_f16 v[16:19], v[164:167], v[216:219], v[16:19]
	v_mfma_f32_16x16x32_f16 v[60:63], v[160:163], v[196:199], v[60:63]
	v_mfma_f32_16x16x32_f16 v[56:59], v[172:175], v[196:199], v[56:59]
	v_mfma_f32_16x16x32_f16 v[52:55], v[160:163], v[204:207], v[52:55]
	v_mfma_f32_16x16x32_f16 v[48:51], v[172:175], v[204:207], v[48:51]
	v_mfma_f32_16x16x32_f16 v[36:39], v[160:163], v[212:215], v[36:39]
	v_mfma_f32_16x16x32_f16 v[32:35], v[172:175], v[212:215], v[32:35]
	v_mfma_f32_16x16x32_f16 v[20:23], v[160:163], v[220:223], v[20:23]
	v_mfma_f32_16x16x32_f16 v[16:19], v[172:175], v[220:223], v[16:19]
	s_setprio 0
	s_setprio 1
	v_mfma_f32_16x16x32_f16 v[44:47], v[176:179], v[192:195], v[44:47]
	v_mfma_f32_16x16x32_f16 v[40:43], v[184:187], v[192:195], v[40:43]
	v_mfma_f32_16x16x32_f16 v[28:31], v[176:179], v[200:203], v[28:31]
	v_mfma_f32_16x16x32_f16 v[24:27], v[184:187], v[200:203], v[24:27]
	v_mfma_f32_16x16x32_f16 v[12:15], v[176:179], v[208:211], v[12:15]
	v_mfma_f32_16x16x32_f16 v[8:11], v[184:187], v[208:211], v[8:11]
	v_mfma_f32_16x16x32_f16 v[4:7], v[176:179], v[216:219], v[4:7]
	v_mfma_f32_16x16x32_f16 v[0:3], v[184:187], v[216:219], v[0:3]
	v_mfma_f32_16x16x32_f16 v[44:47], v[180:183], v[196:199], v[44:47]
	v_mfma_f32_16x16x32_f16 v[40:43], v[188:191], v[196:199], v[40:43]
	v_mfma_f32_16x16x32_f16 v[28:31], v[180:183], v[204:207], v[28:31]
	v_mfma_f32_16x16x32_f16 v[24:27], v[188:191], v[204:207], v[24:27]
	v_mfma_f32_16x16x32_f16 v[12:15], v[180:183], v[212:215], v[12:15]
	v_mfma_f32_16x16x32_f16 v[8:11], v[188:191], v[212:215], v[8:11]
	v_mfma_f32_16x16x32_f16 v[4:7], v[180:183], v[220:223], v[4:7]
	v_mfma_f32_16x16x32_f16 v[0:3], v[188:191], v[220:223], v[0:3]
	s_setprio 0
	s_barrier
	s_add_i32 s2, 0, 0x18000
	v_add_u32_e32 v155, s2, v151
	s_add_i32 s3, 0, 0x1c000
	ds_read_b128 v[156:159], v155
	ds_read_b128 v[160:163], v155 offset:1024
	ds_read_b128 v[164:167], v155 offset:2048
	ds_read_b128 v[172:175], v155 offset:3072
	v_add_u32_e32 v155, s3, v151
	ds_read_b128 v[176:179], v155
	ds_read_b128 v[180:183], v155 offset:1024
	ds_read_b128 v[184:187], v155 offset:2048
	ds_read_b128 v[188:191], v155 offset:3072
	s_add_u32 s50, s50, 0x40000
	s_addc_u32 s51, s51, 0
	s_mov_b32 m0, s17
	ds_read_b128 v[192:195], v154 offset:32768
	ds_read_b128 v[196:199], v154 offset:33792
	ds_read_b128 v[200:203], v154 offset:34816
	ds_read_b128 v[204:207], v154 offset:35840
	ds_read_b128 v[208:211], v154 offset:36864
	ds_read_b128 v[212:215], v154 offset:37888
	ds_read_b128 v[216:219], v154 offset:38912
	ds_read_b128 v[220:223], v154 offset:39936
	global_load_lds_dwordx4 v138, s[50:51]
	s_mov_b32 m0, s18
	s_nop 0
	global_load_lds_dwordx4 v132, s[50:51]
	s_waitcnt vmcnt(8)
	s_waitcnt lgkmcnt(0)
	v_mfma_f32_16x16x32_f16 v[124:127], v[156:159], v[192:195], v[124:127]
	v_mfma_f32_16x16x32_f16 v[120:123], v[164:167], v[192:195], v[120:123]
	v_mfma_f32_16x16x32_f16 v[116:119], v[156:159], v[200:203], v[116:119]
	v_mfma_f32_16x16x32_f16 v[108:111], v[164:167], v[200:203], v[108:111]
	s_barrier
	s_setprio 1
	s_waitcnt lgkmcnt(0)
	v_mfma_f32_16x16x32_f16 v[100:103], v[156:159], v[208:211], v[100:103]
	v_mfma_f32_16x16x32_f16 v[92:95], v[164:167], v[208:211], v[92:95]
	v_mfma_f32_16x16x32_f16 v[84:87], v[156:159], v[216:219], v[84:87]
	v_mfma_f32_16x16x32_f16 v[76:79], v[164:167], v[216:219], v[76:79]
	v_mfma_f32_16x16x32_f16 v[124:127], v[160:163], v[196:199], v[124:127]
	v_mfma_f32_16x16x32_f16 v[120:123], v[172:175], v[196:199], v[120:123]
	v_mfma_f32_16x16x32_f16 v[116:119], v[160:163], v[204:207], v[116:119]
	v_mfma_f32_16x16x32_f16 v[108:111], v[172:175], v[204:207], v[108:111]
	v_mfma_f32_16x16x32_f16 v[100:103], v[160:163], v[212:215], v[100:103]
	v_mfma_f32_16x16x32_f16 v[92:95], v[172:175], v[212:215], v[92:95]
	v_mfma_f32_16x16x32_f16 v[84:87], v[160:163], v[220:223], v[84:87]
	v_mfma_f32_16x16x32_f16 v[76:79], v[172:175], v[220:223], v[76:79]
	s_setprio 0
	s_setprio 1
	v_mfma_f32_16x16x32_f16 v[112:115], v[176:179], v[192:195], v[112:115]
	v_mfma_f32_16x16x32_f16 v[104:107], v[184:187], v[192:195], v[104:107]
	v_mfma_f32_16x16x32_f16 v[96:99], v[176:179], v[200:203], v[96:99]
	v_mfma_f32_16x16x32_f16 v[88:91], v[184:187], v[200:203], v[88:91]
	v_mfma_f32_16x16x32_f16 v[80:83], v[176:179], v[208:211], v[80:83]
	v_mfma_f32_16x16x32_f16 v[72:75], v[184:187], v[208:211], v[72:75]
	v_mfma_f32_16x16x32_f16 v[68:71], v[176:179], v[216:219], v[68:71]
	v_mfma_f32_16x16x32_f16 v[64:67], v[184:187], v[216:219], v[64:67]
	v_mfma_f32_16x16x32_f16 v[112:115], v[180:183], v[196:199], v[112:115]
	v_mfma_f32_16x16x32_f16 v[104:107], v[188:191], v[196:199], v[104:107]
	v_mfma_f32_16x16x32_f16 v[96:99], v[180:183], v[204:207], v[96:99]
	v_mfma_f32_16x16x32_f16 v[88:91], v[188:191], v[204:207], v[88:91]
	v_mfma_f32_16x16x32_f16 v[80:83], v[180:183], v[212:215], v[80:83]
	v_mfma_f32_16x16x32_f16 v[72:75], v[188:191], v[212:215], v[72:75]
	v_mfma_f32_16x16x32_f16 v[68:71], v[180:183], v[220:223], v[68:71]
	v_mfma_f32_16x16x32_f16 v[64:67], v[188:191], v[220:223], v[64:67]
	s_setprio 0
	s_barrier
	s_add_i32 s2, s2, s14
	s_add_u32 s56, s56, 0x80
	s_addc_u32 s57, s57, 0
	s_add_u32 s50, s50, 0xfffc0080
	s_addc_u32 s51, s51, -1
	s_mov_b32 m0, s2
	ds_read_b128 v[192:195], v154 offset:49152
	ds_read_b128 v[196:199], v154 offset:50176
	ds_read_b128 v[200:203], v154 offset:51200
	ds_read_b128 v[204:207], v154 offset:52224
	ds_read_b128 v[208:211], v154 offset:53248
	ds_read_b128 v[212:215], v154 offset:54272
	ds_read_b128 v[216:219], v154 offset:55296
	ds_read_b128 v[220:223], v154 offset:56320
	global_load_lds_dwordx4 v136, s[56:57]
	s_add_i32 m0, s2, 0x2000
	s_add_i32 s2, s3, s14
	global_load_lds_dwordx4 v130, s[56:57]
	s_mov_b32 m0, s2
	s_nop 0
	global_load_lds_dwordx4 v134, s[56:57]
	s_add_i32 m0, s2, 0x2000
	s_nop 0
	global_load_lds_dwordx4 v128, s[56:57]
	s_mov_b32 m0, s19
	s_nop 0
	global_load_lds_dwordx4 v138, s[50:51]
	s_mov_b32 m0, s20
	s_nop 0
	global_load_lds_dwordx4 v132, s[50:51]
	s_waitcnt vmcnt(8)
	s_waitcnt lgkmcnt(0)
	v_mfma_f32_16x16x32_f16 v[60:63], v[156:159], v[192:195], v[60:63]
	v_mfma_f32_16x16x32_f16 v[56:59], v[164:167], v[192:195], v[56:59]
	v_mfma_f32_16x16x32_f16 v[52:55], v[156:159], v[200:203], v[52:55]
	v_mfma_f32_16x16x32_f16 v[48:51], v[164:167], v[200:203], v[48:51]
	s_barrier
	s_setprio 1
	s_waitcnt lgkmcnt(0)
	v_mfma_f32_16x16x32_f16 v[36:39], v[156:159], v[208:211], v[36:39]
	v_mfma_f32_16x16x32_f16 v[32:35], v[164:167], v[208:211], v[32:35]
	v_mfma_f32_16x16x32_f16 v[20:23], v[156:159], v[216:219], v[20:23]
	v_mfma_f32_16x16x32_f16 v[16:19], v[164:167], v[216:219], v[16:19]
	v_mfma_f32_16x16x32_f16 v[60:63], v[160:163], v[196:199], v[60:63]
	v_mfma_f32_16x16x32_f16 v[56:59], v[172:175], v[196:199], v[56:59]
	v_mfma_f32_16x16x32_f16 v[52:55], v[160:163], v[204:207], v[52:55]
	v_mfma_f32_16x16x32_f16 v[48:51], v[172:175], v[204:207], v[48:51]
	v_mfma_f32_16x16x32_f16 v[36:39], v[160:163], v[212:215], v[36:39]
	v_mfma_f32_16x16x32_f16 v[32:35], v[172:175], v[212:215], v[32:35]
	v_mfma_f32_16x16x32_f16 v[20:23], v[160:163], v[220:223], v[20:23]
	v_mfma_f32_16x16x32_f16 v[16:19], v[172:175], v[220:223], v[16:19]
	s_setprio 0
	s_setprio 1
	v_mfma_f32_16x16x32_f16 v[44:47], v[176:179], v[192:195], v[44:47]
	v_mfma_f32_16x16x32_f16 v[40:43], v[184:187], v[192:195], v[40:43]
	v_mfma_f32_16x16x32_f16 v[28:31], v[176:179], v[200:203], v[28:31]
	v_mfma_f32_16x16x32_f16 v[24:27], v[184:187], v[200:203], v[24:27]
	v_mfma_f32_16x16x32_f16 v[12:15], v[176:179], v[208:211], v[12:15]
	v_mfma_f32_16x16x32_f16 v[8:11], v[184:187], v[208:211], v[8:11]
	v_mfma_f32_16x16x32_f16 v[4:7], v[176:179], v[216:219], v[4:7]
	v_mfma_f32_16x16x32_f16 v[0:3], v[184:187], v[216:219], v[0:3]
	v_mfma_f32_16x16x32_f16 v[44:47], v[180:183], v[196:199], v[44:47]
	v_mfma_f32_16x16x32_f16 v[40:43], v[188:191], v[196:199], v[40:43]
	v_mfma_f32_16x16x32_f16 v[28:31], v[180:183], v[204:207], v[28:31]
	v_mfma_f32_16x16x32_f16 v[24:27], v[188:191], v[204:207], v[24:27]
	v_mfma_f32_16x16x32_f16 v[12:15], v[180:183], v[212:215], v[12:15]
	v_mfma_f32_16x16x32_f16 v[8:11], v[188:191], v[212:215], v[8:11]
	v_mfma_f32_16x16x32_f16 v[4:7], v[180:183], v[220:223], v[4:7]
	v_mfma_f32_16x16x32_f16 v[0:3], v[188:191], v[220:223], v[0:3]
	s_setprio 0
	s_barrier
	s_add_i32 s55, s55, 2
	s_add_u32 s48, s48, 0x100
	s_addc_u32 s49, s49, 0
	s_add_u32 s53, s53, 0x100
	s_addc_u32 s54, s54, 0
	s_cmp_gt_u32 s55, 13
	s_cbranch_scc0 .LBB0_629
	s_and_b64 vcc, exec, s[22:23]
	s_cbranch_vccz .LBB0_632
	s_barrier

.LBB0_649:
	ds_read_b128 v[160:163], v156
	ds_read_b128 v[164:167], v156 offset:1024
	ds_read_b128 v[172:175], v156 offset:2048
	ds_read_b128 v[176:179], v156 offset:3072
	ds_read_b128 v[180:183], v157
	ds_read_b128 v[184:187], v157 offset:1024
	ds_read_b128 v[188:191], v157 offset:2048
	ds_read_b128 v[192:195], v157 offset:3072
	s_add_u32 s2, s44, 0xfffc0080
	s_addc_u32 s3, s45, -1
	s_cmp_eq_u32 s52, 12
	s_cselect_b32 s47, s27, s3
	s_cselect_b32 s46, s48, s2
	s_cselect_b32 s55, s25, s51
	s_cselect_b32 s54, s49, s50
	s_add_i32 m0, s15, 0xc000
	ds_read_b128 v[196:199], v158
	ds_read_b128 v[200:203], v158 offset:1024
	ds_read_b128 v[204:207], v158 offset:2048
	ds_read_b128 v[208:211], v158 offset:3072
	ds_read_b128 v[212:215], v158 offset:4096
	ds_read_b128 v[216:219], v158 offset:5120
	ds_read_b128 v[220:223], v158 offset:6144
	ds_read_b128 v[224:227], v158 offset:7168
	global_load_lds_dwordx4 v142, s[44:45]
	s_add_i32 m0, s15, 0xe000
	s_nop 0
	global_load_lds_dwordx4 v144, s[44:45]
	s_waitcnt vmcnt(8)
	s_waitcnt lgkmcnt(0)
	v_mfma_f32_16x16x32_f16 v[124:127], v[160:163], v[196:199], v[124:127]
	v_mfma_f32_16x16x32_f16 v[120:123], v[172:175], v[196:199], v[120:123]
	v_mfma_f32_16x16x32_f16 v[116:119], v[160:163], v[204:207], v[116:119]
	v_mfma_f32_16x16x32_f16 v[108:111], v[172:175], v[204:207], v[108:111]
	s_barrier
	s_setprio 1
	s_waitcnt lgkmcnt(0)
	v_mfma_f32_16x16x32_f16 v[100:103], v[160:163], v[212:215], v[100:103]
	v_mfma_f32_16x16x32_f16 v[92:95], v[172:175], v[212:215], v[92:95]
	v_mfma_f32_16x16x32_f16 v[84:87], v[160:163], v[220:223], v[84:87]
	v_mfma_f32_16x16x32_f16 v[76:79], v[172:175], v[220:223], v[76:79]
	v_mfma_f32_16x16x32_f16 v[124:127], v[164:167], v[200:203], v[124:127]
	v_mfma_f32_16x16x32_f16 v[120:123], v[176:179], v[200:203], v[120:123]
	v_mfma_f32_16x16x32_f16 v[116:119], v[164:167], v[208:211], v[116:119]
	v_mfma_f32_16x16x32_f16 v[108:111], v[176:179], v[208:211], v[108:111]
	v_mfma_f32_16x16x32_f16 v[100:103], v[164:167], v[216:219], v[100:103]
	v_mfma_f32_16x16x32_f16 v[92:95], v[176:179], v[216:219], v[92:95]
	v_mfma_f32_16x16x32_f16 v[84:87], v[164:167], v[224:227], v[84:87]
	v_mfma_f32_16x16x32_f16 v[76:79], v[176:179], v[224:227], v[76:79]
	s_setprio 0
	s_setprio 1
	v_mfma_f32_16x16x32_f16 v[112:115], v[180:183], v[196:199], v[112:115]
	v_mfma_f32_16x16x32_f16 v[104:107], v[188:191], v[196:199], v[104:107]
	v_mfma_f32_16x16x32_f16 v[96:99], v[180:183], v[204:207], v[96:99]
	v_mfma_f32_16x16x32_f16 v[88:91], v[188:191], v[204:207], v[88:91]
	v_mfma_f32_16x16x32_f16 v[80:83], v[180:183], v[212:215], v[80:83]
	v_mfma_f32_16x16x32_f16 v[72:75], v[188:191], v[212:215], v[72:75]
	v_mfma_f32_16x16x32_f16 v[68:71], v[180:183], v[220:223], v[68:71]
	v_mfma_f32_16x16x32_f16 v[64:67], v[188:191], v[220:223], v[64:67]
	v_mfma_f32_16x16x32_f16 v[112:115], v[184:187], v[200:203], v[112:115]
	v_mfma_f32_16x16x32_f16 v[104:107], v[192:195], v[200:203], v[104:107]
	v_mfma_f32_16x16x32_f16 v[96:99], v[184:187], v[208:211], v[96:99]
	v_mfma_f32_16x16x32_f16 v[88:91], v[192:195], v[208:211], v[88:91]
	v_mfma_f32_16x16x32_f16 v[80:83], v[184:187], v[216:219], v[80:83]
	v_mfma_f32_16x16x32_f16 v[72:75], v[192:195], v[216:219], v[72:75]
	v_mfma_f32_16x16x32_f16 v[68:71], v[184:187], v[224:227], v[68:71]
	v_mfma_f32_16x16x32_f16 v[64:67], v[192:195], v[224:227], v[64:67]
	s_setprio 0
	s_barrier
	s_add_i32 s2, s21, s14
	s_mov_b32 m0, s2
	ds_read_b128 v[196:199], v158 offset:16384
	ds_read_b128 v[200:203], v158 offset:17408
	ds_read_b128 v[204:207], v158 offset:18432
	ds_read_b128 v[208:211], v158 offset:19456
	ds_read_b128 v[212:215], v158 offset:20480
	ds_read_b128 v[216:219], v158 offset:21504
	ds_read_b128 v[220:223], v158 offset:22528
	ds_read_b128 v[224:227], v158 offset:23552
	global_load_lds_dwordx4 v136, s[54:55]
	s_add_i32 m0, s2, 0x2000
	s_add_i32 s2, s28, s14
	global_load_lds_dwordx4 v130, s[54:55]
	s_mov_b32 m0, s2
	s_nop 0
	global_load_lds_dwordx4 v134, s[54:55]
	s_add_i32 m0, s2, 0x2000
	s_nop 0
	global_load_lds_dwordx4 v128, s[54:55]
	s_mov_b32 m0, s15
	s_nop 0
	global_load_lds_dwordx4 v138, s[46:47]
	s_mov_b32 m0, s16
	s_nop 0
	global_load_lds_dwordx4 v132, s[46:47]
	s_waitcnt vmcnt(8)
	s_waitcnt lgkmcnt(0)
	v_mfma_f32_16x16x32_f16 v[60:63], v[160:163], v[196:199], v[60:63]
	v_mfma_f32_16x16x32_f16 v[56:59], v[172:175], v[196:199], v[56:59]
	v_mfma_f32_16x16x32_f16 v[52:55], v[160:163], v[204:207], v[52:55]
	v_mfma_f32_16x16x32_f16 v[48:51], v[172:175], v[204:207], v[48:51]
	s_barrier
	s_setprio 1
	s_waitcnt lgkmcnt(0)
	v_mfma_f32_16x16x32_f16 v[36:39], v[160:163], v[212:215], v[36:39]
	v_mfma_f32_16x16x32_f16 v[32:35], v[172:175], v[212:215], v[32:35]
	v_mfma_f32_16x16x32_f16 v[20:23], v[160:163], v[220:223], v[20:23]
	v_mfma_f32_16x16x32_f16 v[16:19], v[172:175], v[220:223], v[16:19]
	v_mfma_f32_16x16x32_f16 v[60:63], v[164:167], v[200:203], v[60:63]
	v_mfma_f32_16x16x32_f16 v[56:59], v[176:179], v[200:203], v[56:59]
	v_mfma_f32_16x16x32_f16 v[52:55], v[164:167], v[208:211], v[52:55]
	v_mfma_f32_16x16x32_f16 v[48:51], v[176:179], v[208:211], v[48:51]
	v_mfma_f32_16x16x32_f16 v[36:39], v[164:167], v[216:219], v[36:39]
	v_mfma_f32_16x16x32_f16 v[32:35], v[176:179], v[216:219], v[32:35]
	v_mfma_f32_16x16x32_f16 v[20:23], v[164:167], v[224:227], v[20:23]
	v_mfma_f32_16x16x32_f16 v[16:19], v[176:179], v[224:227], v[16:19]
	s_setprio 0
	s_setprio 1
	v_mfma_f32_16x16x32_f16 v[44:47], v[180:183], v[196:199], v[44:47]
	v_mfma_f32_16x16x32_f16 v[40:43], v[188:191], v[196:199], v[40:43]
	v_mfma_f32_16x16x32_f16 v[28:31], v[180:183], v[204:207], v[28:31]
	v_mfma_f32_16x16x32_f16 v[24:27], v[188:191], v[204:207], v[24:27]
	v_mfma_f32_16x16x32_f16 v[12:15], v[180:183], v[212:215], v[12:15]
	v_mfma_f32_16x16x32_f16 v[8:11], v[188:191], v[212:215], v[8:11]
	v_mfma_f32_16x16x32_f16 v[4:7], v[180:183], v[220:223], v[4:7]
	v_mfma_f32_16x16x32_f16 v[0:3], v[188:191], v[220:223], v[0:3]
	v_mfma_f32_16x16x32_f16 v[44:47], v[184:187], v[200:203], v[44:47]
	v_mfma_f32_16x16x32_f16 v[40:43], v[192:195], v[200:203], v[40:43]
	v_mfma_f32_16x16x32_f16 v[28:31], v[184:187], v[208:211], v[28:31]
	v_mfma_f32_16x16x32_f16 v[24:27], v[192:195], v[208:211], v[24:27]
	v_mfma_f32_16x16x32_f16 v[12:15], v[184:187], v[216:219], v[12:15]
	v_mfma_f32_16x16x32_f16 v[8:11], v[192:195], v[216:219], v[8:11]
	v_mfma_f32_16x16x32_f16 v[4:7], v[184:187], v[224:227], v[4:7]
	v_mfma_f32_16x16x32_f16 v[0:3], v[192:195], v[224:227], v[0:3]
	s_setprio 0
	s_barrier
	s_add_i32 s2, 0, 0x18000
	v_add_u32_e32 v151, s2, v155
	s_add_i32 s3, 0, 0x1c000
	ds_read_b128 v[160:163], v151
	ds_read_b128 v[164:167], v151 offset:1024
	ds_read_b128 v[172:175], v151 offset:2048
	ds_read_b128 v[176:179], v151 offset:3072
	v_add_u32_e32 v151, s3, v155
	ds_read_b128 v[180:183], v151
	ds_read_b128 v[184:187], v151 offset:1024
	ds_read_b128 v[188:191], v151 offset:2048
	ds_read_b128 v[192:195], v151 offset:3072
	s_add_u32 s46, s46, 0x40000
	s_addc_u32 s47, s47, 0
	s_mov_b32 m0, s17
	ds_read_b128 v[196:199], v158 offset:32768
	ds_read_b128 v[200:203], v158 offset:33792
	ds_read_b128 v[204:207], v158 offset:34816
	ds_read_b128 v[208:211], v158 offset:35840
	ds_read_b128 v[212:215], v158 offset:36864
	ds_read_b128 v[216:219], v158 offset:37888
	ds_read_b128 v[220:223], v158 offset:38912
	ds_read_b128 v[224:227], v158 offset:39936
	global_load_lds_dwordx4 v138, s[46:47]
	s_mov_b32 m0, s18
	s_nop 0
	global_load_lds_dwordx4 v132, s[46:47]
	s_waitcnt vmcnt(8)
	s_waitcnt lgkmcnt(0)
	v_mfma_f32_16x16x32_f16 v[124:127], v[160:163], v[196:199], v[124:127]
	v_mfma_f32_16x16x32_f16 v[120:123], v[172:175], v[196:199], v[120:123]
	v_mfma_f32_16x16x32_f16 v[116:119], v[160:163], v[204:207], v[116:119]
	v_mfma_f32_16x16x32_f16 v[108:111], v[172:175], v[204:207], v[108:111]
	s_barrier
	s_setprio 1
	s_waitcnt lgkmcnt(0)
	v_mfma_f32_16x16x32_f16 v[100:103], v[160:163], v[212:215], v[100:103]
	v_mfma_f32_16x16x32_f16 v[92:95], v[172:175], v[212:215], v[92:95]
	v_mfma_f32_16x16x32_f16 v[84:87], v[160:163], v[220:223], v[84:87]
	v_mfma_f32_16x16x32_f16 v[76:79], v[172:175], v[220:223], v[76:79]
	v_mfma_f32_16x16x32_f16 v[124:127], v[164:167], v[200:203], v[124:127]
	v_mfma_f32_16x16x32_f16 v[120:123], v[176:179], v[200:203], v[120:123]
	v_mfma_f32_16x16x32_f16 v[116:119], v[164:167], v[208:211], v[116:119]
	v_mfma_f32_16x16x32_f16 v[108:111], v[176:179], v[208:211], v[108:111]
	v_mfma_f32_16x16x32_f16 v[100:103], v[164:167], v[216:219], v[100:103]
	v_mfma_f32_16x16x32_f16 v[92:95], v[176:179], v[216:219], v[92:95]
	v_mfma_f32_16x16x32_f16 v[84:87], v[164:167], v[224:227], v[84:87]
	v_mfma_f32_16x16x32_f16 v[76:79], v[176:179], v[224:227], v[76:79]
	s_setprio 0
	s_setprio 1
	v_mfma_f32_16x16x32_f16 v[112:115], v[180:183], v[196:199], v[112:115]
	v_mfma_f32_16x16x32_f16 v[104:107], v[188:191], v[196:199], v[104:107]
	v_mfma_f32_16x16x32_f16 v[96:99], v[180:183], v[204:207], v[96:99]
	v_mfma_f32_16x16x32_f16 v[88:91], v[188:191], v[204:207], v[88:91]
	v_mfma_f32_16x16x32_f16 v[80:83], v[180:183], v[212:215], v[80:83]
	v_mfma_f32_16x16x32_f16 v[72:75], v[188:191], v[212:215], v[72:75]
	v_mfma_f32_16x16x32_f16 v[68:71], v[180:183], v[220:223], v[68:71]
	v_mfma_f32_16x16x32_f16 v[64:67], v[188:191], v[220:223], v[64:67]
	v_mfma_f32_16x16x32_f16 v[112:115], v[184:187], v[200:203], v[112:115]
	v_mfma_f32_16x16x32_f16 v[104:107], v[192:195], v[200:203], v[104:107]
	v_mfma_f32_16x16x32_f16 v[96:99], v[184:187], v[208:211], v[96:99]
	v_mfma_f32_16x16x32_f16 v[88:91], v[192:195], v[208:211], v[88:91]
	v_mfma_f32_16x16x32_f16 v[80:83], v[184:187], v[216:219], v[80:83]
	v_mfma_f32_16x16x32_f16 v[72:75], v[192:195], v[216:219], v[72:75]
	v_mfma_f32_16x16x32_f16 v[68:71], v[184:187], v[224:227], v[68:71]
	v_mfma_f32_16x16x32_f16 v[64:67], v[192:195], v[224:227], v[64:67]
	s_setprio 0
	s_barrier
	s_add_i32 s2, s2, s14
	s_add_u32 s54, s54, 0x80
	s_addc_u32 s55, s55, 0
	s_add_u32 s46, s46, 0xfffc0080
	s_addc_u32 s47, s47, -1
	s_mov_b32 m0, s2
	ds_read_b128 v[196:199], v158 offset:49152
	ds_read_b128 v[200:203], v158 offset:50176
	ds_read_b128 v[204:207], v158 offset:51200
	ds_read_b128 v[208:211], v158 offset:52224
	ds_read_b128 v[212:215], v158 offset:53248
	ds_read_b128 v[216:219], v158 offset:54272
	ds_read_b128 v[220:223], v158 offset:55296
	ds_read_b128 v[224:227], v158 offset:56320
	global_load_lds_dwordx4 v136, s[54:55]
	s_add_i32 m0, s2, 0x2000
	s_add_i32 s2, s3, s14
	global_load_lds_dwordx4 v130, s[54:55]
	s_mov_b32 m0, s2
	s_nop 0
	global_load_lds_dwordx4 v134, s[54:55]
	s_add_i32 m0, s2, 0x2000
	s_nop 0
	global_load_lds_dwordx4 v128, s[54:55]
	s_mov_b32 m0, s19
	s_nop 0
	global_load_lds_dwordx4 v138, s[46:47]
	s_mov_b32 m0, s20
	s_nop 0
	global_load_lds_dwordx4 v132, s[46:47]
	s_waitcnt vmcnt(8)
	s_waitcnt lgkmcnt(0)
	v_mfma_f32_16x16x32_f16 v[60:63], v[160:163], v[196:199], v[60:63]
	v_mfma_f32_16x16x32_f16 v[56:59], v[172:175], v[196:199], v[56:59]
	v_mfma_f32_16x16x32_f16 v[52:55], v[160:163], v[204:207], v[52:55]
	v_mfma_f32_16x16x32_f16 v[48:51], v[172:175], v[204:207], v[48:51]
	s_barrier
	s_setprio 1
	s_waitcnt lgkmcnt(0)
	v_mfma_f32_16x16x32_f16 v[36:39], v[160:163], v[212:215], v[36:39]
	v_mfma_f32_16x16x32_f16 v[32:35], v[172:175], v[212:215], v[32:35]
	v_mfma_f32_16x16x32_f16 v[20:23], v[160:163], v[220:223], v[20:23]
	v_mfma_f32_16x16x32_f16 v[16:19], v[172:175], v[220:223], v[16:19]
	v_mfma_f32_16x16x32_f16 v[60:63], v[164:167], v[200:203], v[60:63]
	v_mfma_f32_16x16x32_f16 v[56:59], v[176:179], v[200:203], v[56:59]
	v_mfma_f32_16x16x32_f16 v[52:55], v[164:167], v[208:211], v[52:55]
	v_mfma_f32_16x16x32_f16 v[48:51], v[176:179], v[208:211], v[48:51]
	v_mfma_f32_16x16x32_f16 v[36:39], v[164:167], v[216:219], v[36:39]
	v_mfma_f32_16x16x32_f16 v[32:35], v[176:179], v[216:219], v[32:35]
	v_mfma_f32_16x16x32_f16 v[20:23], v[164:167], v[224:227], v[20:23]
	v_mfma_f32_16x16x32_f16 v[16:19], v[176:179], v[224:227], v[16:19]
	s_setprio 0
	s_setprio 1
	v_mfma_f32_16x16x32_f16 v[44:47], v[180:183], v[196:199], v[44:47]
	v_mfma_f32_16x16x32_f16 v[40:43], v[188:191], v[196:199], v[40:43]
	v_mfma_f32_16x16x32_f16 v[28:31], v[180:183], v[204:207], v[28:31]
	v_mfma_f32_16x16x32_f16 v[24:27], v[188:191], v[204:207], v[24:27]
	v_mfma_f32_16x16x32_f16 v[12:15], v[180:183], v[212:215], v[12:15]
	v_mfma_f32_16x16x32_f16 v[8:11], v[188:191], v[212:215], v[8:11]
	v_mfma_f32_16x16x32_f16 v[4:7], v[180:183], v[220:223], v[4:7]
	v_mfma_f32_16x16x32_f16 v[0:3], v[188:191], v[220:223], v[0:3]
	v_mfma_f32_16x16x32_f16 v[44:47], v[184:187], v[200:203], v[44:47]
	v_mfma_f32_16x16x32_f16 v[40:43], v[192:195], v[200:203], v[40:43]
	v_mfma_f32_16x16x32_f16 v[28:31], v[184:187], v[208:211], v[28:31]
	v_mfma_f32_16x16x32_f16 v[24:27], v[192:195], v[208:211], v[24:27]
	v_mfma_f32_16x16x32_f16 v[12:15], v[184:187], v[216:219], v[12:15]
	v_mfma_f32_16x16x32_f16 v[8:11], v[192:195], v[216:219], v[8:11]
	v_mfma_f32_16x16x32_f16 v[4:7], v[184:187], v[224:227], v[4:7]
	v_mfma_f32_16x16x32_f16 v[0:3], v[192:195], v[224:227], v[0:3]
	s_setprio 0
	s_barrier
	s_add_i32 s52, s52, 2
	s_add_u32 s44, s44, 0x100
	s_addc_u32 s45, s45, 0
	s_add_u32 s50, s50, 0x100
	s_addc_u32 s51, s51, 0
	s_cmp_gt_u32 s52, 13
	s_cbranch_scc0 .LBB0_649
	s_and_b64 vcc, exec, s[22:23]
	s_cbranch_vccz .LBB0_652
	s_barrier

.LBB0_737:
	s_add_i32 s5, s4, 8
	s_lshl_b32 s7, s4, 1
	s_lshl_b32 s1, s4, 3
	s_lshl_b32 s2, s4, 10
	s_lshl_b32 s3, s5, 3
	s_lshl_b32 s10, s5, 10
	s_lshl_b32 s11, s4, 2
	s_lshl_b32 s12, s5, 2
	s_and_b32 s13, s0, 0x70
	s_add_i32 s8, s7, 2
	s_add_i32 s9, s7, 4
	s_add_i32 s14, s7, 6
	s_add_i32 s5, s5, s4
	s_add_i32 s15, s7, 10
	s_add_i32 s16, s7, 12
	s_add_i32 s17, s7, 14
	s_cmp_gt_u32 s7, 0xffffffef
	s_mov_b32 s94, 0x8000
	s_cselect_b32 s6, s94, 0x10000
	s_mov_b32 s29, 0x18000
	s_cselect_b32 s18, 0x18000, 0
	s_cselect_b32 s39, 0, 0x8000
	v_writelane_b32 v255, s6, 24
	s_cselect_b32 s6, 0x10000, s29
	s_cmp_lt_u32 s17, 16
	v_writelane_b32 v255, s6, 40
	s_cselect_b32 s21, 0x18000, 0
	s_cselect_b32 s30, 0, 0x8000
	s_cselect_b32 s46, s94, 0x10000
	s_cselect_b32 s6, 0x10000, s29
	s_cmp_lt_u32 s16, 16
	v_writelane_b32 v254, s6, 58
	s_cselect_b32 s25, 0x18000, 0
	s_cselect_b32 s28, 0, 0x8000
	s_cselect_b32 s45, s94, 0x10000
	s_cselect_b32 s6, 0x10000, s29
	s_cmp_lt_u32 s15, 16
	v_writelane_b32 v254, s6, 59
	s_cselect_b32 s35, 0x18000, 0
	s_cselect_b32 s36, 0, 0x8000
	s_cselect_b32 s44, s94, 0x10000
	s_cselect_b32 s6, 0x10000, s29
	s_cmp_lt_u32 s5, 16
	s_cselect_b32 s37, 0x18000, 0
	s_cselect_b32 s47, 0, 0x8000
	s_cselect_b32 s48, s94, 0x10000
	s_cselect_b32 s49, 0x10000, s29
	s_cmp_lt_u32 s14, 16
	s_cselect_b32 s31, 0x18000, 0
	s_cselect_b32 s50, 0, 0x8000
	s_cselect_b32 s51, s94, 0x10000
	s_cselect_b32 s52, 0x10000, s29
	s_cmp_lt_u32 s9, 16
	s_cselect_b32 s34, 0x18000, 0
	s_cselect_b32 s55, 0, 0x8000
	s_cselect_b32 s56, s94, 0x10000
	s_cselect_b32 s57, 0x10000, s29
	s_cmp_lt_u32 s8, 16
	s_cselect_b32 s26, 0x18000, 0
	s_cselect_b32 s58, 0, 0x8000
	s_cselect_b32 s59, s94, 0x10000
	s_cselect_b32 s60, 0x10000, s29
	s_cmp_lt_u32 s7, 16
	s_cselect_b32 s27, 0x18000, 0
	s_cselect_b32 s61, 0, 0x8000
	s_cselect_b32 s62, s94, 0x10000
	s_cselect_b32 vcc_lo, 0x10000, s29
	s_cmp_gt_i32 s4, -1
	s_cselect_b32 s64, 0x10000, s94
	s_cselect_b32 vcc_hi, s29, 0x10000
	s_cmp_gt_i32 s4, 0
	s_cselect_b32 s38, 0, 0x18000
	s_cselect_b32 s63, 0x8000, 0
	s_cselect_b32 s66, 0x10000, s94
	s_cselect_b32 s24, s29, 0x10000
	s_cmp_gt_i32 s4, 1
	s_cselect_b32 s53, 0, 0x18000
	s_cselect_b32 s65, 0x8000, 0
	s_cselect_b32 s68, 0x10000, s94
	s_cselect_b32 s80, s29, 0x10000
	s_cmp_gt_i32 s4, 2
	s_cselect_b32 s54, 0, 0x18000
	s_cselect_b32 s67, 0x8000, 0
	s_cselect_b32 s71, 0x10000, s94
	s_cselect_b32 s82, s29, 0x10000
	s_cmp_gt_i32 s4, 3
	s_cselect_b32 s69, 0, 0x18000
	s_cselect_b32 s70, 0x8000, 0
	s_cselect_b32 s75, 0x10000, s94
	s_cselect_b32 s83, s29, 0x10000
	s_cmp_gt_i32 s4, 4
	s_cselect_b32 s74, 0, 0x18000
	s_cselect_b32 s76, 0x8000, 0
	s_cselect_b32 s77, 0x10000, s94
	s_cselect_b32 s84, s29, 0x10000
	s_cmp_gt_i32 s4, 5
	s_cselect_b32 s78, 0, 0x18000
	s_cselect_b32 s85, 0x8000, 0
	s_cselect_b32 s92, 0x10000, s94
	s_cselect_b32 s86, s29, 0x10000
	s_cmp_gt_i32 s4, 6
	s_cselect_b32 s87, 0, 0x18000
	s_cselect_b32 s88, 0x8000, 0
	s_cselect_b32 s91, 0x10000, s94
	s_cselect_b32 s97, s29, 0x10000
	s_cmp_gt_i32 s4, 7
	v_writelane_b32 v255, s6, 25
	s_cselect_b32 s90, 0, 0x18000
	s_cselect_b32 s93, 0x8000, 0
	s_cselect_b32 s94, 0x10000, s94
	s_cselect_b32 s6, s29, 0x10000
	s_add_i32 s27, s27, 0
	v_writelane_b32 v253, s27, 4
	s_add_i32 s26, s26, 0
	v_writelane_b32 v253, s26, 1
	s_and_b32 s26, s7, 14
	s_add_i32 s7, s34, 0
	v_writelane_b32 v253, s7, 13
	s_add_i32 s7, s31, 0
	v_writelane_b32 v253, s7, 2
	s_add_i32 s7, s37, 0
	v_writelane_b32 v255, s7, 6
	s_add_i32 s7, s35, 0
	v_writelane_b32 v255, s7, 7
	s_and_b32 s37, s5, 14
	s_add_i32 s5, s25, 0
	v_writelane_b32 v255, s5, 8
	s_add_i32 s5, s21, 0
	v_writelane_b32 v255, s5, 9
	s_add_i32 s5, s18, 0
	v_writelane_b32 v255, s5, 10
	s_add_i32 s5, s93, 0
	v_writelane_b32 v255, s5, 11
	s_add_i32 s5, s88, 0
	v_writelane_b32 v255, s5, 12
	s_add_i32 s5, s85, 0
	v_writelane_b32 v255, s5, 13
	s_add_i32 s5, s76, 0
	v_writelane_b32 v255, s5, 14
	s_add_i32 s5, s70, 0
	v_writelane_b32 v255, s5, 15
	s_add_i32 s5, s67, 0
	v_writelane_b32 v255, s5, 16
	s_add_i32 s5, s65, 0
	v_writelane_b32 v255, s5, 17
	s_add_i32 s5, s63, 0
	v_writelane_b32 v255, s5, 18
	s_add_i32 s5, s0, 16
	v_writelane_b32 v255, s5, 34
	s_and_b32 s65, s5, 0x70
	s_add_i32 s5, s0, 32
	v_writelane_b32 v255, s5, 35
	s_and_b32 s67, s5, 0x70
	s_add_i32 s5, s0, 48
	s_add_i32 s29, s69, 0
	v_writelane_b32 v255, s5, 36
	s_and_b32 s69, s5, 0x70
	s_add_i32 s5, s0, 0x50
	s_add_i32 s95, s74, 0
	s_add_i32 s20, s38, 0
	s_ashr_i32 s38, s4, 31
	v_writelane_b32 v255, s5, 37
	s_and_b32 s74, s5, 0x70
	s_add_i32 s5, s0, 0x60
	s_and_b32 s38, s38, 0x18000
	v_writelane_b32 v255, s5, 38
	s_and_b32 s76, s5, 0x70
	s_add_i32 s5, s0, 0x70
	s_add_i32 s79, s90, 0
	s_add_i32 s87, s87, 0
	s_add_i32 s89, s78, 0
	s_add_i32 s96, s54, 0
	s_add_i32 s19, s53, 0
	s_add_i32 s23, s38, 0
	s_and_b32 s27, s8, 14
	s_and_b32 s31, s9, 14
	s_and_b32 s34, s14, 14
	s_and_b32 s38, s15, 14
	s_and_b32 s53, s16, 14
	s_and_b32 s54, s17, 14
	s_xor_b32 s70, s13, 64
	s_and_b32 s78, s5, 0x70
	s_cmp_lt_i32 s4, 0
	s_cselect_b32 s4, 0, 0x8000
	v_writelane_b32 v255, s5, 39
	s_add_i32 s4, s4, 0
	v_writelane_b32 v255, s4, 19
	s_add_i32 s4, s61, 0
	v_writelane_b32 v255, s4, 20
	s_add_i32 s4, s58, 0
	v_writelane_b32 v255, s4, 21
	s_add_i32 s4, s55, 0
	v_writelane_b32 v255, s4, 22
	s_add_i32 s4, s50, 0
	v_writelane_b32 v255, s4, 23
	s_add_i32 s4, s47, 0
	v_writelane_b32 v255, s4, 28
	s_add_i32 s4, s36, 0
	v_writelane_b32 v255, s4, 29
	s_add_i32 s4, s28, 0
	v_writelane_b32 v255, s4, 30
	s_add_i32 s4, s30, 0
	v_writelane_b32 v255, s4, 31
	s_add_i32 s4, s39, 0
	v_bfe_u32 v63, v0, 4, 2
	v_writelane_b32 v255, s4, 32
	v_readlane_b32 s4, v253, 8
	v_lshlrev_b32_e32 v2, 3, v63
	v_readlane_b32 s5, v253, 9
	s_add_i32 s16, s6, 0
	s_add_i32 s36, s52, 0
	v_lshl_add_u64 v[22:23], s[4:5], 0, v[2:3]
	s_add_i32 s4, s94, 0
	v_writelane_b32 v255, s4, 33
	s_add_i32 s88, s66, 0
	v_readlane_b32 s6, v255, 25
	s_add_i32 s52, s6, 0
	v_readlane_b32 s6, v254, 59
	s_add_i32 s55, s6, 0
	v_readlane_b32 s6, v254, 58
	s_add_i32 s66, s56, 0
	s_add_i32 s56, s6, 0
	v_readlane_b32 s6, v255, 40
	s_add_i32 s35, s57, 0
	s_add_i32 s57, s6, 0
	v_readlane_b32 s6, v253, 36
	v_and_b32_e32 v62, 63, v0
	v_readlane_b32 s7, v255, 24
	v_mov_b32_e32 v27, s6
	v_readlane_b32 s6, v254, 17
	v_lshlrev_b32_e32 v20, 2, v63
	s_add_i32 s91, s91, 0
	s_add_i32 s92, s92, 0
	s_add_i32 s93, s77, 0
	s_add_i32 s94, s75, 0
	s_add_i32 s63, s71, 0
	s_add_i32 s85, s68, 0
	s_add_i32 s4, s64, 0
	s_add_i32 s5, s62, 0
	s_add_i32 s64, s59, 0
	s_add_i32 s68, s51, 0
	s_add_i32 s71, s48, 0
	s_add_i32 s75, s44, 0
	s_add_i32 s77, s45, 0
	s_add_i32 s14, s46, 0
	s_add_i32 s15, s7, 0
	s_add_i32 s17, s97, 0
	s_add_i32 s18, s86, 0
	s_add_i32 s97, s84, 0
	s_mov_b32 s84, s87
	s_add_i32 s90, s83, 0
	s_add_i32 s21, s82, 0
	s_add_i32 s80, s80, 0
	s_add_i32 s24, s24, 0
	s_add_i32 s25, vcc_hi, 0
	s_add_i32 s28, vcc_lo, 0
	s_add_i32 s30, s60, 0
	s_add_i32 s39, s49, 0
	v_mov_b32_e32 v2, 0
	v_mov_b32_e32 v28, 0
	s_mov_b32 s59, 0
	s_add_i32 s58, s0, s6
	v_cmp_gt_u32_e64 s[6:7], 16, v62
	s_mov_b64 s[46:47], 0
	s_mov_b64 s[44:45], -1
	v_readlane_b32 s48, v254, 15
	s_mov_b32 s8, 0
	v_readlane_b32 s49, v254, 16
.LBB0_738:
	s_waitcnt vmcnt(0) lgkmcnt(0)
	s_mov_b32 s79, 0x3e38aa3b
	s_mov_b32 s77, 0xc000
	s_mov_b32 s78, 0xffffc000
	v_readlane_b32 s1, v253, 23
	v_readfirstlane_b32 s0, v170
	s_nop 3
	s_lshr_b32 s0, s0, 6
	s_and_b32 s74, s1, 7
	s_lshl_b32 s74, s74, 5
	s_lshr_b32 s75, s1, 3
	s_add_u32 s74, s74, s75
	s_lshl_b32 s74, s74, 3
	s_and_b32 s4, s74, 31
	s_lshr_b32 s75, s74, 5
	s_and_b32 s5, s75, 0
	s_lshr_b32 s75, s75, 0
	s_and_b32 s3, s75, 3
	s_lshr_b32 s2, s75, 2
	s_sub_u32 s6, 8, s0
	s_lshl_b32 s70, s0, 10
	s_lshl_b32 s74, s2, 21
	s_lshl_b32 s75, s3, 19
	s_add_u32 s74, s74, s75
	s_add_u32 s34, s40, s74
	s_addc_u32 s35, s41, 0
	s_mov_b32 s30, s34
	s_mov_b32 s31, s35
	s_lshl_b32 s74, s2, 16
	s_lshl_b32 s75, s3, 14
	s_add_u32 s74, s74, s75
	s_add_u32 s74, s74, 0xc000000
	s_add_u32 s58, s42, s74
	s_addc_u32 s59, s43, 0
	s_add_u32 s74, s2, 0
	s_lshl_b32 s74, s74, 2
	s_add_u32 s74, s74, s3
	s_lshl_b32 s74, s74, 19
	s_add_u32 s60, s42, s74
	s_addc_u32 s61, s43, 0
	s_lshl_b32 s74, s2, 6
	s_add_u32 s74, s74, 0
	s_lshl_b32 s74, s74, 15
	s_lshl_b32 s75, s3, 13
	s_add_u32 s74, s74, s75
	s_add_u32 s74, s74, 0x6000000
	s_add_u32 s64, s42, s74
	s_addc_u32 s65, s43, 0
	v_and_b32_e32 v141, 63, v170
	v_and_b32_e32 v241, 15, v141
	v_lshrrev_b32_e32 v242, 4, v141
	v_mov_b32_e32 v244, 0xf149f2ca
	v_mov_b32_e32 v248, 0
	v_mov_b32_e32 v249, 0
	v_lshrrev_b32_e32 v142, 1, v241
	v_xor_b32_e32 v142, v142, v242
	v_lshlrev_b32_e32 v142, 4, v142
	v_lshl_add_u32 v142, v241, 7, v142
	s_lshl_b32 s74, s0, 11
	v_add_u32_e32 v230, s74, v142
	v_xor_b32_e32 v231, 64, v230
	v_lshrrev_b32_e32 v142, 1, v242
	v_xor_b32_e32 v243, v142, v241
	v_and_b32_e32 v142, 1, v242
	v_lshlrev_b32_e32 v142, 3, v142
	v_lshl_add_u32 v142, v241, 8, v142
	v_add_u32_e32 v142, 0x10000, v142
	s_add_u32 s74, s0, 0
	s_and_b32 s75, s74, 7
	s_lshl_b32 s75, s75, 1
	s_lshr_b32 s74, s74, 3
	s_lshl_b32 s74, s74, 14
	v_xor_b32_e32 v143, s75, v243
	v_lshl_add_u32 v143, v143, 4, v142
	v_add_u32_e32 v221, s74, v143
	s_add_u32 s74, s0, 1
	s_and_b32 s75, s74, 7
	s_lshl_b32 s75, s75, 1
	s_lshr_b32 s74, s74, 3
	s_lshl_b32 s74, s74, 14
	v_xor_b32_e32 v143, s75, v243
	v_lshl_add_u32 v143, v143, 4, v142
	v_add_u32_e32 v222, s74, v143
	s_add_u32 s74, s0, 2
	s_and_b32 s75, s74, 7
	s_lshl_b32 s75, s75, 1
	s_lshr_b32 s74, s74, 3
	s_lshl_b32 s74, s74, 14
	v_xor_b32_e32 v143, s75, v243
	v_lshl_add_u32 v143, v143, 4, v142
	v_add_u32_e32 v223, s74, v143
	s_add_u32 s74, s0, 3
	s_and_b32 s75, s74, 7
	s_lshl_b32 s75, s75, 1
	s_lshr_b32 s74, s74, 3
	s_lshl_b32 s74, s74, 14
	v_xor_b32_e32 v143, s75, v243
	v_lshl_add_u32 v143, v143, 4, v142
	v_add_u32_e32 v224, s74, v143
	s_add_u32 s74, s0, 4
	s_and_b32 s75, s74, 7
	s_lshl_b32 s75, s75, 1
	s_lshr_b32 s74, s74, 3
	s_lshl_b32 s74, s74, 14
	v_xor_b32_e32 v143, s75, v243
	v_lshl_add_u32 v143, v143, 4, v142
	v_add_u32_e32 v225, s74, v143
	s_add_u32 s74, s0, 5
	s_and_b32 s75, s74, 7
	s_lshl_b32 s75, s75, 1
	s_lshr_b32 s74, s74, 3
	s_lshl_b32 s74, s74, 14
	v_xor_b32_e32 v143, s75, v243
	v_lshl_add_u32 v143, v143, 4, v142
	v_add_u32_e32 v226, s74, v143
	s_add_u32 s74, s0, 6
	s_and_b32 s75, s74, 7
	s_lshl_b32 s75, s75, 1
	s_lshr_b32 s74, s74, 3
	s_lshl_b32 s74, s74, 14
	v_xor_b32_e32 v143, s75, v243
	v_lshl_add_u32 v143, v143, 4, v142
	v_add_u32_e32 v227, s74, v143
	s_add_u32 s74, s0, 7
	s_and_b32 s75, s74, 7
	s_lshl_b32 s75, s75, 1
	s_lshr_b32 s74, s74, 3
	s_lshl_b32 s74, s74, 14
	v_xor_b32_e32 v143, s75, v243
	v_lshl_add_u32 v143, v143, 4, v142
	v_add_u32_e32 v228, s74, v143
	s_add_u32 s74, s0, 8
	s_and_b32 s75, s74, 7
	s_lshl_b32 s75, s75, 1
	s_lshr_b32 s74, s74, 3
	s_lshl_b32 s74, s74, 14
	v_xor_b32_e32 v143, s75, v243
	v_lshl_add_u32 v143, v143, 4, v142
	v_add_u32_e32 v229, s74, v143
	s_and_b32 s74, s0, 1
	s_lshl_b32 s74, s74, 2
	v_add_u32_e32 v142, s74, v242
	v_and_b32_e32 v143, 7, v141
	v_xor_b32_e32 v142, v142, v143
	v_lshlrev_b32_e32 v142, 4, v142
	v_lshrrev_b32_e32 v143, 3, v141
	s_lshl_b32 s74, s0, 3
	v_add_u32_e32 v143, s74, v143
	v_lshl_add_u32 v232, v143, 7, v142
	v_add_u32_e32 v233, 0x2000, v232
	s_and_b32 s74, s0, 3
	s_lshl_b32 s74, s74, 2
	v_add_u32_e32 v142, s74, v242
	v_xor_b32_e32 v142, v142, v241
	v_lshlrev_b32_e32 v142, 4, v142
	s_lshl_b32 s74, s0, 2
	v_add_u32_e32 v143, s74, v242
	v_lshl_add_u32 v234, v143, 15, v142
	v_add_u32_e32 v235, 0x100000, v234
	s_lshl_b32 s74, s0, 4
	v_add_u32_e32 v142, s74, v241
	v_lshlrev_b32_e32 v142, 0, v142
	v_lshlrev_b32_e32 v238, 2, v142
	v_lshlrev_b32_e32 v142, 7, v142
	v_lshl_add_u32 v236, v242, 4, v142
	v_lshl_add_u32 v237, v242, 3, v142
	v_xor_b32_e32 v142, 16, v141
	v_lshlrev_b32_e32 v239, 2, v142
	v_xor_b32_e32 v142, 32, v141
	v_lshlrev_b32_e32 v240, 2, v142
	s_add_u32 s74, s2, 1
	v_cvt_f32_u32_e32 v142, s74
	v_mul_f32_e32 v142, 0xc1000000, v142
	v_mul_f32_e32 v142, 0x3caaaaab, v142
	v_exp_f32_e32 v142, v142
	v_lshlrev_b32_e32 v144, 2, v242
	v_sub_u32_e32 v145, v241, v144
	v_mul_f32_e32 v142, 0x3f800000, v142
	v_add_u32_e32 v145, 0x80, v145
	v_mul_f32_e32 v142, 0x3fb8aa3b, v142
	v_cvt_f32_i32_e32 v145, v145
	s_nop 0
	v_mul_f32_e64 v143, -v142, v145
	v_fmamk_f32 v185, v142, 0x0, v143
	v_fmamk_f32 v186, v142, 0x3f800000, v143
	v_fmamk_f32 v187, v142, 0x40000000, v143
	v_fmamk_f32 v188, v142, 0x40400000, v143
	v_fmamk_f32 v189, v142, 0x41800000, v143
	v_fmamk_f32 v190, v142, 0x41880000, v143
	v_fmamk_f32 v191, v142, 0x41900000, v143
	v_fmamk_f32 v192, v142, 0x41980000, v143
	v_fmamk_f32 v193, v142, 0x42000000, v143
	v_fmamk_f32 v194, v142, 0x42040000, v143
	v_fmamk_f32 v195, v142, 0x42080000, v143
	v_fmamk_f32 v196, v142, 0x420c0000, v143
	v_fmamk_f32 v197, v142, 0x42400000, v143
	v_fmamk_f32 v198, v142, 0x42440000, v143
	v_fmamk_f32 v199, v142, 0x42480000, v143
	v_fmamk_f32 v200, v142, 0x424c0000, v143
	v_fmamk_f32 v201, v142, 0x42800000, v143
	v_fmamk_f32 v202, v142, 0x42820000, v143
	v_fmamk_f32 v203, v142, 0x42840000, v143
	v_fmamk_f32 v204, v142, 0x42860000, v143
	v_fmamk_f32 v205, v142, 0x42a00000, v143
	v_fmamk_f32 v206, v142, 0x42a20000, v143
	v_fmamk_f32 v207, v142, 0x42a40000, v143
	v_fmamk_f32 v208, v142, 0x42a60000, v143
	v_fmamk_f32 v209, v142, 0x42c00000, v143
	v_fmamk_f32 v210, v142, 0x42c20000, v143
	v_fmamk_f32 v211, v142, 0x42c40000, v143
	v_fmamk_f32 v212, v142, 0x42c60000, v143
	v_fmamk_f32 v213, v142, 0x42e00000, v143
	v_fmamk_f32 v214, v142, 0x42e20000, v143
	v_fmamk_f32 v215, v142, 0x42e40000, v143
	v_fmamk_f32 v216, v142, 0x42e60000, v143
	v_fmamk_f32 v217, v142, 0x43000000, v143
	v_fmamk_f32 v218, v142, 0x43010000, v143
	v_fmamk_f32 v219, v142, 0x43020000, v143
	v_fmamk_f32 v220, v142, 0x43030000, v143
	v_add_u32_e32 v145, 0, v144
	v_cmp_lt_u32_e32 vcc, v145, v241
	s_nop 1
	v_cndmask_b32_e32 v185, v185, v244, vcc
	v_cmp_gt_u32_e32 vcc, v145, v241
	s_nop 1
	v_cndmask_b32_e32 v217, v217, v244, vcc
	v_add_u32_e32 v145, 1, v144
	v_cmp_lt_u32_e32 vcc, v145, v241
	s_nop 1
	v_cndmask_b32_e32 v186, v186, v244, vcc
	v_cmp_gt_u32_e32 vcc, v145, v241
	s_nop 1
	v_cndmask_b32_e32 v218, v218, v244, vcc
	v_add_u32_e32 v145, 2, v144
	v_cmp_lt_u32_e32 vcc, v145, v241
	s_nop 1
	v_cndmask_b32_e32 v187, v187, v244, vcc
	v_cmp_gt_u32_e32 vcc, v145, v241
	s_nop 1
	v_cndmask_b32_e32 v219, v219, v244, vcc
	v_add_u32_e32 v145, 3, v144
	v_cmp_lt_u32_e32 vcc, v145, v241
	s_nop 1
	v_cndmask_b32_e32 v188, v188, v244, vcc
	v_cmp_gt_u32_e32 vcc, v145, v241
	s_nop 1
	v_cndmask_b32_e32 v220, v220, v244, vcc
	s_lshl_b32 s74, s4, 7
	s_add_u32 s74, s74, s5
	s_lshl_b32 s75, s74, 7
	s_add_u32 s10, s30, s75
	s_addc_u32 s11, s31, 0
	s_add_u32 s86, s34, s75
	s_addc_u32 s87, s35, 0
	s_lshl_b32 s75, s74, 2
	s_add_u32 s88, s58, s75
	s_addc_u32 s89, s59, 0
	global_load_dwordx4 v[96:99], v236, s[10:11]
	global_load_dwordx4 v[100:103], v236, s[10:11] offset:64
	s_mov_b32 s7, 0
	s_nop 0
